# EpiAct (P1 and P6) epilogues hand-packed: v_pk f32 math, row scales via LDS DMA
# speedup vs baseline: 1.0680x; 1.0030x over previous
; __device__ __forceinline__ void row_rs8(const float* SS, int row0, int fq, float (&rsv)[2][4]) {
;     f32x4 q[2][4];
; #pragma unroll
;     for (int ai = 0; ai < 2; ++ai)
; #pragma unroll
;         for (int m = 0; m < 4; ++m) q[ai][m] = *(const f32x4*)(SS + (size_t)(row0 + ai * HALF + m * 16) * 16 + 4 * fq);
; #pragma unroll
;     for (int ai = 0; ai < 2; ++ai)
; #pragma unroll
;         for (int m = 0; m < 4; ++m) { float t = (q[ai][m][0] + q[ai][m][1]) + (q[ai][m][2] + q[ai][m][3]); t += __shfl_xor(t, 16); t += __shfl_xor(t, 32); rsv[ai][m] = __builtin_amdgcn_rsqf(t * (1.0f / 1024.0f) + 1e-6f); }
; }
;     __device__ __forceinline__ void operator()(const f32x4 (&acc)[2][2][4][2], const Unit& u, int wr, int wc, int fr, int fq) const {
;         const int row0 = u.pm * BM + wr * 64 + fr, col0 = u.pn * HALF + wc * 32 + 8 * fq;
;         float rsv[2][4]; row_rs8(SS, row0, fq, rsv);
; #pragma unroll
;         for (int ai = 0; ai < 2; ++ai)
; #pragma unroll
;             for (int m = 0; m < 4; ++m) {
;                 const int r = row0 + ai * HALF + m * 16; const float rs = rsv[ai][m], nrs = rs * -1.4426950408889634f, rs2 = rs * rs;
;                 float o[8];
; #pragma unroll
;                 for (int n = 0; n < 2; ++n) {
;                     const f32x4 t = acc[ai][0][m][n] * nrs, p = (acc[ai][0][m][n] * acc[ai][1][m][n]) * rs2;
.LBB0_267:
	v_lshl_add_u32 v162, s4, 8, v129
	v_and_b32_e32 v244, 48, v192
	v_lshl_add_u32 v244, v129, 6, v244
	v_add_u32_e32 v244, 0x20000, v244
	ds_read_b128 v[174:177], v244
	ds_read_b128 v[178:181], v244 offset:1024
	ds_read_b128 v[182:185], v244 offset:2048
	ds_read_b128 v[186:189], v244 offset:3072
	ds_read_b128 v[194:197], v244 offset:8192
	ds_read_b128 v[198:201], v244 offset:9216
	ds_read_b128 v[202:205], v244 offset:10240
	ds_read_b128 v[206:209], v244 offset:11264
	v_xor_b32_e32 v210, 16, v171
	v_xor_b32_e32 v211, 32, v171
	v_lshlrev_b32_e32 v210, 2, v210
	v_lshlrev_b32_e32 v211, 2, v211
	v_or_b32_e32 v160, 16, v162
	v_or_b32_e32 v158, 32, v162
	v_or_b32_e32 v156, 48, v162
	v_add_u32_e32 v154, 0x80, v162
	v_add_u32_e32 v152, 0x90, v162
	v_add_u32_e32 v150, 0xa0, v162
	v_add_u32_e32 v148, 0xb0, v162
	v_lshl_or_b32 v242, s5, 7, v167
	v_lshlrev_b32_e32 v242, 1, v242
	v_mov_b32_e32 v243, 0
	v_mov_b64_e32 v[220:221], s[52:53]
	s_and_b64 vcc, exec, s[6:7]
	s_mov_b64 s[6:7], -1
	v_pk_mul_f32 v[124:125], v[124:125], v[120:121]
	v_pk_mul_f32 v[126:127], v[126:127], v[122:123]
	v_pk_mul_f32 v[112:113], v[112:113], v[116:117]
	v_pk_mul_f32 v[114:115], v[114:115], v[118:119]
	v_pk_mul_f32 v[104:105], v[104:105], v[108:109]
	v_pk_mul_f32 v[106:107], v[106:107], v[110:111]
	v_pk_mul_f32 v[96:97], v[96:97], v[100:101]
	v_pk_mul_f32 v[98:99], v[98:99], v[102:103]
	v_pk_mul_f32 v[88:89], v[88:89], v[92:93]
	v_pk_mul_f32 v[90:91], v[90:91], v[94:95]
	v_pk_mul_f32 v[80:81], v[80:81], v[84:85]
	v_pk_mul_f32 v[82:83], v[82:83], v[86:87]
	v_pk_mul_f32 v[72:73], v[72:73], v[76:77]
	v_pk_mul_f32 v[74:75], v[74:75], v[78:79]
	v_pk_mul_f32 v[64:65], v[64:65], v[68:69]
	v_pk_mul_f32 v[66:67], v[66:67], v[70:71]
	v_pk_mul_f32 v[56:57], v[56:57], v[60:61]
	v_pk_mul_f32 v[58:59], v[58:59], v[62:63]
	v_pk_mul_f32 v[48:49], v[48:49], v[52:53]
	v_pk_mul_f32 v[50:51], v[50:51], v[54:55]
	v_pk_mul_f32 v[40:41], v[40:41], v[44:45]
	v_pk_mul_f32 v[42:43], v[42:43], v[46:47]
	v_pk_mul_f32 v[32:33], v[32:33], v[36:37]
	v_pk_mul_f32 v[34:35], v[34:35], v[38:39]
	v_pk_mul_f32 v[24:25], v[24:25], v[28:29]
	v_pk_mul_f32 v[26:27], v[26:27], v[30:31]
	v_pk_mul_f32 v[16:17], v[16:17], v[20:21]
	v_pk_mul_f32 v[18:19], v[18:19], v[22:23]
	v_pk_mul_f32 v[8:9], v[8:9], v[12:13]
	v_pk_mul_f32 v[10:11], v[10:11], v[14:15]
	v_pk_mul_f32 v[0:1], v[0:1], v[4:5]
	v_pk_mul_f32 v[2:3], v[2:3], v[6:7]
	s_waitcnt lgkmcnt(0)
	v_pk_add_f32 v[174:175], v[174:175], v[176:177]
	v_pk_add_f32 v[178:179], v[178:179], v[180:181]
	v_pk_add_f32 v[182:183], v[182:183], v[184:185]
	v_pk_add_f32 v[186:187], v[186:187], v[188:189]
	v_pk_add_f32 v[194:195], v[194:195], v[196:197]
	v_pk_add_f32 v[198:199], v[198:199], v[200:201]
	v_pk_add_f32 v[202:203], v[202:203], v[204:205]
	v_pk_add_f32 v[206:207], v[206:207], v[208:209]
	v_add_f32_e32 v212, v174, v175
	v_add_f32_e32 v213, v178, v179
	v_add_f32_e32 v214, v182, v183
	v_add_f32_e32 v215, v186, v187
	v_add_f32_e32 v216, v194, v195
	v_add_f32_e32 v217, v198, v199
	v_add_f32_e32 v218, v202, v203
	v_add_f32_e32 v219, v206, v207
	ds_bpermute_b32 v222, v210, v212
	ds_bpermute_b32 v223, v210, v213
	ds_bpermute_b32 v224, v210, v214
	ds_bpermute_b32 v225, v210, v215
	ds_bpermute_b32 v226, v210, v216
	ds_bpermute_b32 v227, v210, v217
	ds_bpermute_b32 v228, v210, v218
	ds_bpermute_b32 v229, v210, v219
	s_waitcnt lgkmcnt(7)
	v_add_f32_e32 v212, v212, v222
	s_waitcnt lgkmcnt(6)
	v_add_f32_e32 v213, v213, v223
	s_waitcnt lgkmcnt(5)
	v_add_f32_e32 v214, v214, v224
	s_waitcnt lgkmcnt(4)
	v_add_f32_e32 v215, v215, v225
	s_waitcnt lgkmcnt(3)
	v_add_f32_e32 v216, v216, v226
	s_waitcnt lgkmcnt(2)
	v_add_f32_e32 v217, v217, v227
	s_waitcnt lgkmcnt(1)
	v_add_f32_e32 v218, v218, v228
	s_waitcnt lgkmcnt(0)
	v_add_f32_e32 v219, v219, v229
	ds_bpermute_b32 v222, v211, v212
	ds_bpermute_b32 v223, v211, v213
	ds_bpermute_b32 v224, v211, v214
	ds_bpermute_b32 v225, v211, v215
	ds_bpermute_b32 v226, v211, v216
	ds_bpermute_b32 v227, v211, v217
	ds_bpermute_b32 v228, v211, v218
	ds_bpermute_b32 v229, v211, v219
	s_waitcnt lgkmcnt(7)
	v_add_f32_e32 v212, v212, v222
	s_waitcnt lgkmcnt(6)
	v_add_f32_e32 v213, v213, v223
	s_waitcnt lgkmcnt(5)
	v_add_f32_e32 v214, v214, v224
	s_waitcnt lgkmcnt(4)
	v_add_f32_e32 v215, v215, v225
	s_waitcnt lgkmcnt(3)
	v_add_f32_e32 v216, v216, v226
	s_waitcnt lgkmcnt(2)
	v_add_f32_e32 v217, v217, v227
	s_waitcnt lgkmcnt(1)
	v_add_f32_e32 v218, v218, v228
	s_waitcnt lgkmcnt(0)
; __device__ __forceinline__ unsigned cvt_pk_bf16(float lo, float hi) { unsigned r; asm volatile("v_cvt_pk_bf16_f32 %0, %1, %2" : "=v"(r) : "v"(lo), "v"(hi)); return r; }
; __device__ __forceinline__ float fast_rcp(float x) { return __builtin_amdgcn_rcpf(x); }
; __device__ __forceinline__ unsigned cvt_pk_bf16(float lo, float hi) { const f32x2 v = {lo, hi}; const bf16x2_t b = __builtin_convertvector(v, bf16x2_t); return __builtin_bit_cast(unsigned, b); }
; __device__ __forceinline__ void row_rs8(const float* SS, int row0, int fq, float (&rsv)[2][4]) {
;     ...
;         for (int m = 0; m < 4; ++m) { float t = (q[ai][m][0] + q[ai][m][1]) + (q[ai][m][2] + q[ai][m][3]); t += __shfl_xor(t, 16); t += __shfl_xor(t, 32); rsv[ai][m] = __builtin_amdgcn_rsqf(t * (1.0f / 1024.0f) + 1e-6f); }
;     __device__ __forceinline__ void operator()(const f32x4 (&acc)[2][2][4][2], const Unit& u, int wr, int wc, int fr, int fq) const {
;     ...
;                 const int r = row0 + ai * HALF + m * 16; const float rs = rsv[ai][m], nrs = rs * -1.4426950408889634f, rs2 = rs * rs;
;                 float o[8];
; #pragma unroll
;                 for (int n = 0; n < 2; ++n) {
;                     const f32x4 t = acc[ai][0][m][n] * nrs, p = (acc[ai][0][m][n] * acc[ai][1][m][n]) * rs2;
; #pragma unroll
;                     for (int j = 0; j < 4; ++j) o[4 * n + j] = p[j] * fast_rcp(1.0f + __builtin_amdgcn_exp2f(t[j]));
;                 }
;                 u32x4 w; w.x = cvt_pk_bf16(o[0], o[1]); w.y = cvt_pk_bf16(o[2], o[3]); w.z = cvt_pk_bf16(o[4], o[5]); w.w = cvt_pk_bf16(o[6], o[7]);
;                 *(u32x4*)(O + (size_t)r * ldo + col0) = w;
	v_add_f32_e32 v219, v219, v229
	v_fmamk_f32 v212, v212, 0x3a800000, v172
	v_fmamk_f32 v213, v213, 0x3a800000, v172
	v_fmamk_f32 v214, v214, 0x3a800000, v172
	v_fmamk_f32 v215, v215, 0x3a800000, v172
	v_fmamk_f32 v216, v216, 0x3a800000, v172
	v_fmamk_f32 v217, v217, 0x3a800000, v172
	v_fmamk_f32 v218, v218, 0x3a800000, v172
	v_fmamk_f32 v219, v219, 0x3a800000, v172
	v_rsq_f32_e32 v212, v212
	v_rsq_f32_e32 v213, v213
	v_rsq_f32_e32 v214, v214
	v_rsq_f32_e32 v215, v215
	v_rsq_f32_e32 v216, v216
	v_rsq_f32_e32 v217, v217
	v_rsq_f32_e32 v218, v218
	v_rsq_f32_e32 v219, v219
	v_mul_f32_e32 v230, 0xbfb8aa3b, v212
	v_mul_f32_e32 v231, v212, v212
	v_mul_f32_e32 v232, 0xbfb8aa3b, v213
	v_mul_f32_e32 v233, v213, v213
	v_mul_f32_e32 v234, 0xbfb8aa3b, v214
	v_mul_f32_e32 v235, v214, v214
	v_mul_f32_e32 v184, 0xbfb8aa3b, v215
	v_mul_f32_e32 v185, v215, v215
	v_mul_f32_e32 v186, 0xbfb8aa3b, v216
	v_mul_f32_e32 v187, v216, v216
	v_mul_f32_e32 v188, 0xbfb8aa3b, v217
	v_mul_f32_e32 v189, v217, v217
	v_mul_f32_e32 v190, 0xbfb8aa3b, v218
	v_mul_f32_e32 v191, v218, v218
	v_mul_f32_e32 v204, 0xbfb8aa3b, v219
	v_mul_f32_e32 v205, v219, v219
	v_pk_mul_f32 v[120:121], v[120:121], v[230:231] op_sel_hi:[1,0]
	v_pk_mul_f32 v[122:123], v[122:123], v[230:231] op_sel_hi:[1,0]
	v_pk_mul_f32 v[116:117], v[116:117], v[230:231] op_sel_hi:[1,0]
	v_pk_mul_f32 v[118:119], v[118:119], v[230:231] op_sel_hi:[1,0]
	v_exp_f32_e32 v120, v120
	v_exp_f32_e32 v121, v121
	v_exp_f32_e32 v122, v122
	v_exp_f32_e32 v123, v123
	v_exp_f32_e32 v116, v116
	v_exp_f32_e32 v117, v117
	v_exp_f32_e32 v118, v118
	v_exp_f32_e32 v119, v119
	v_pk_mul_f32 v[124:125], v[124:125], v[230:231] op_sel:[0,1] op_sel_hi:[1,1]
	v_pk_mul_f32 v[126:127], v[126:127], v[230:231] op_sel:[0,1] op_sel_hi:[1,1]
	v_pk_mul_f32 v[112:113], v[112:113], v[230:231] op_sel:[0,1] op_sel_hi:[1,1]
	v_pk_mul_f32 v[114:115], v[114:115], v[230:231] op_sel:[0,1] op_sel_hi:[1,1]
	v_pk_add_f32 v[120:121], v[120:121], 1.0 op_sel_hi:[1,0]
	v_pk_add_f32 v[122:123], v[122:123], 1.0 op_sel_hi:[1,0]
	v_pk_add_f32 v[116:117], v[116:117], 1.0 op_sel_hi:[1,0]
	v_pk_add_f32 v[118:119], v[118:119], 1.0 op_sel_hi:[1,0]
	v_rcp_f32_e32 v120, v120
	v_rcp_f32_e32 v121, v121
	v_rcp_f32_e32 v122, v122
	v_rcp_f32_e32 v123, v123
	v_rcp_f32_e32 v116, v116
	v_rcp_f32_e32 v117, v117
	v_rcp_f32_e32 v118, v118
	v_rcp_f32_e32 v119, v119
	v_mad_i64_i32 v[208:209], s[4:5], v162, s68, v[220:221]
	v_lshl_add_u64 v[208:209], v[208:209], 0, v[242:243]
	v_pk_mul_f32 v[124:125], v[124:125], v[120:121]
	v_pk_mul_f32 v[126:127], v[126:127], v[122:123]
	v_pk_mul_f32 v[112:113], v[112:113], v[116:117]
	v_pk_mul_f32 v[114:115], v[114:115], v[118:119]
	v_cvt_pk_bf16_f32 v120, v124, v125
	v_cvt_pk_bf16_f32 v121, v126, v127
	v_cvt_pk_bf16_f32 v122, v112, v113
	v_cvt_pk_bf16_f32 v123, v114, v115
	global_store_dwordx4 v[208:209], v[120:123], off
	v_pk_mul_f32 v[108:109], v[108:109], v[232:233] op_sel_hi:[1,0]
	v_pk_mul_f32 v[110:111], v[110:111], v[232:233] op_sel_hi:[1,0]
	v_pk_mul_f32 v[100:101], v[100:101], v[232:233] op_sel_hi:[1,0]
	v_pk_mul_f32 v[102:103], v[102:103], v[232:233] op_sel_hi:[1,0]
	v_exp_f32_e32 v108, v108
	v_exp_f32_e32 v109, v109
	v_exp_f32_e32 v110, v110
	v_exp_f32_e32 v111, v111
	v_exp_f32_e32 v100, v100
	v_exp_f32_e32 v101, v101
	v_exp_f32_e32 v102, v102
	v_exp_f32_e32 v103, v103
	v_pk_mul_f32 v[104:105], v[104:105], v[232:233] op_sel:[0,1] op_sel_hi:[1,1]
	v_pk_mul_f32 v[106:107], v[106:107], v[232:233] op_sel:[0,1] op_sel_hi:[1,1]
	v_pk_mul_f32 v[96:97], v[96:97], v[232:233] op_sel:[0,1] op_sel_hi:[1,1]
	v_pk_mul_f32 v[98:99], v[98:99], v[232:233] op_sel:[0,1] op_sel_hi:[1,1]
	v_pk_add_f32 v[108:109], v[108:109], 1.0 op_sel_hi:[1,0]
	v_pk_add_f32 v[110:111], v[110:111], 1.0 op_sel_hi:[1,0]
	v_pk_add_f32 v[100:101], v[100:101], 1.0 op_sel_hi:[1,0]
	v_pk_add_f32 v[102:103], v[102:103], 1.0 op_sel_hi:[1,0]
	v_rcp_f32_e32 v108, v108
	v_rcp_f32_e32 v109, v109
	v_rcp_f32_e32 v110, v110
	v_rcp_f32_e32 v111, v111
	v_rcp_f32_e32 v100, v100
	v_rcp_f32_e32 v101, v101
	v_rcp_f32_e32 v102, v102
	v_rcp_f32_e32 v103, v103
	v_mad_i64_i32 v[208:209], s[4:5], v160, s68, v[220:221]
	v_lshl_add_u64 v[208:209], v[208:209], 0, v[242:243]
	v_pk_mul_f32 v[104:105], v[104:105], v[108:109]
	v_pk_mul_f32 v[106:107], v[106:107], v[110:111]
	v_pk_mul_f32 v[96:97], v[96:97], v[100:101]
	v_pk_mul_f32 v[98:99], v[98:99], v[102:103]
	v_cvt_pk_bf16_f32 v108, v104, v105
	v_cvt_pk_bf16_f32 v109, v106, v107
	v_cvt_pk_bf16_f32 v110, v96, v97
	v_cvt_pk_bf16_f32 v111, v98, v99
	global_store_dwordx4 v[208:209], v[108:111], off
	v_pk_mul_f32 v[92:93], v[92:93], v[234:235] op_sel_hi:[1,0]
	v_pk_mul_f32 v[94:95], v[94:95], v[234:235] op_sel_hi:[1,0]
	v_pk_mul_f32 v[84:85], v[84:85], v[234:235] op_sel_hi:[1,0]
	v_pk_mul_f32 v[86:87], v[86:87], v[234:235] op_sel_hi:[1,0]
	v_exp_f32_e32 v92, v92
	v_exp_f32_e32 v93, v93
	v_exp_f32_e32 v94, v94
	v_exp_f32_e32 v95, v95
	v_exp_f32_e32 v84, v84
	v_exp_f32_e32 v85, v85
	v_exp_f32_e32 v86, v86
	v_exp_f32_e32 v87, v87
	v_pk_mul_f32 v[88:89], v[88:89], v[234:235] op_sel:[0,1] op_sel_hi:[1,1]
	v_pk_mul_f32 v[90:91], v[90:91], v[234:235] op_sel:[0,1] op_sel_hi:[1,1]
	v_pk_mul_f32 v[80:81], v[80:81], v[234:235] op_sel:[0,1] op_sel_hi:[1,1]
	v_pk_mul_f32 v[82:83], v[82:83], v[234:235] op_sel:[0,1] op_sel_hi:[1,1]
	v_pk_add_f32 v[92:93], v[92:93], 1.0 op_sel_hi:[1,0]
	v_pk_add_f32 v[94:95], v[94:95], 1.0 op_sel_hi:[1,0]
	v_pk_add_f32 v[84:85], v[84:85], 1.0 op_sel_hi:[1,0]
	v_pk_add_f32 v[86:87], v[86:87], 1.0 op_sel_hi:[1,0]
	v_rcp_f32_e32 v92, v92
	v_rcp_f32_e32 v93, v93
	v_rcp_f32_e32 v94, v94
	v_rcp_f32_e32 v95, v95
	v_rcp_f32_e32 v84, v84
	v_rcp_f32_e32 v85, v85
; __device__ __forceinline__ unsigned cvt_pk_bf16(float lo, float hi) { unsigned r; asm volatile("v_cvt_pk_bf16_f32 %0, %1, %2" : "=v"(r) : "v"(lo), "v"(hi)); return r; }
; __device__ __forceinline__ float fast_rcp(float x) { return __builtin_amdgcn_rcpf(x); }
; __device__ __forceinline__ unsigned cvt_pk_bf16(float lo, float hi) { const f32x2 v = {lo, hi}; const bf16x2_t b = __builtin_convertvector(v, bf16x2_t); return __builtin_bit_cast(unsigned, b); }
;     __device__ __forceinline__ void operator()(const f32x4 (&acc)[2][2][4][2], const Unit& u, int wr, int wc, int fr, int fq) const {
;     ...
;             for (int m = 0; m < 4; ++m) {
;                 const int r = row0 + ai * HALF + m * 16; const float rs = rsv[ai][m], nrs = rs * -1.4426950408889634f, rs2 = rs * rs;
;                 float o[8];
; #pragma unroll
;                 for (int n = 0; n < 2; ++n) {
;                     const f32x4 t = acc[ai][0][m][n] * nrs, p = (acc[ai][0][m][n] * acc[ai][1][m][n]) * rs2;
; #pragma unroll
;                     for (int j = 0; j < 4; ++j) o[4 * n + j] = p[j] * fast_rcp(1.0f + __builtin_amdgcn_exp2f(t[j]));
;                 }
;                 u32x4 w; w.x = cvt_pk_bf16(o[0], o[1]); w.y = cvt_pk_bf16(o[2], o[3]); w.z = cvt_pk_bf16(o[4], o[5]); w.w = cvt_pk_bf16(o[6], o[7]);
;                 *(u32x4*)(O + (size_t)r * ldo + col0) = w;
	v_rcp_f32_e32 v86, v86
	v_rcp_f32_e32 v87, v87
	v_mad_i64_i32 v[208:209], s[4:5], v158, s68, v[220:221]
	v_lshl_add_u64 v[208:209], v[208:209], 0, v[242:243]
	v_pk_mul_f32 v[88:89], v[88:89], v[92:93]
	v_pk_mul_f32 v[90:91], v[90:91], v[94:95]
	v_pk_mul_f32 v[80:81], v[80:81], v[84:85]
	v_pk_mul_f32 v[82:83], v[82:83], v[86:87]
	v_cvt_pk_bf16_f32 v92, v88, v89
	v_cvt_pk_bf16_f32 v93, v90, v91
	v_cvt_pk_bf16_f32 v94, v80, v81
	v_cvt_pk_bf16_f32 v95, v82, v83
	global_store_dwordx4 v[208:209], v[92:95], off
	v_pk_mul_f32 v[76:77], v[76:77], v[184:185] op_sel_hi:[1,0]
	v_pk_mul_f32 v[78:79], v[78:79], v[184:185] op_sel_hi:[1,0]
	v_pk_mul_f32 v[68:69], v[68:69], v[184:185] op_sel_hi:[1,0]
	v_pk_mul_f32 v[70:71], v[70:71], v[184:185] op_sel_hi:[1,0]
	v_exp_f32_e32 v76, v76
	v_exp_f32_e32 v77, v77
	v_exp_f32_e32 v78, v78
	v_exp_f32_e32 v79, v79
	v_exp_f32_e32 v68, v68
	v_exp_f32_e32 v69, v69
	v_exp_f32_e32 v70, v70
	v_exp_f32_e32 v71, v71
	v_pk_mul_f32 v[72:73], v[72:73], v[184:185] op_sel:[0,1] op_sel_hi:[1,1]
	v_pk_mul_f32 v[74:75], v[74:75], v[184:185] op_sel:[0,1] op_sel_hi:[1,1]
	v_pk_mul_f32 v[64:65], v[64:65], v[184:185] op_sel:[0,1] op_sel_hi:[1,1]
	v_pk_mul_f32 v[66:67], v[66:67], v[184:185] op_sel:[0,1] op_sel_hi:[1,1]
	v_pk_add_f32 v[76:77], v[76:77], 1.0 op_sel_hi:[1,0]
	v_pk_add_f32 v[78:79], v[78:79], 1.0 op_sel_hi:[1,0]
	v_pk_add_f32 v[68:69], v[68:69], 1.0 op_sel_hi:[1,0]
	v_pk_add_f32 v[70:71], v[70:71], 1.0 op_sel_hi:[1,0]
	v_rcp_f32_e32 v76, v76
	v_rcp_f32_e32 v77, v77
	v_rcp_f32_e32 v78, v78
	v_rcp_f32_e32 v79, v79
	v_rcp_f32_e32 v68, v68
	v_rcp_f32_e32 v69, v69
	v_rcp_f32_e32 v70, v70
	v_rcp_f32_e32 v71, v71
	v_mad_i64_i32 v[208:209], s[4:5], v156, s68, v[220:221]
	v_lshl_add_u64 v[208:209], v[208:209], 0, v[242:243]
	v_pk_mul_f32 v[72:73], v[72:73], v[76:77]
	v_pk_mul_f32 v[74:75], v[74:75], v[78:79]
	v_pk_mul_f32 v[64:65], v[64:65], v[68:69]
	v_pk_mul_f32 v[66:67], v[66:67], v[70:71]
	v_cvt_pk_bf16_f32 v76, v72, v73
	v_cvt_pk_bf16_f32 v77, v74, v75
	v_cvt_pk_bf16_f32 v78, v64, v65
	v_cvt_pk_bf16_f32 v79, v66, v67
	global_store_dwordx4 v[208:209], v[76:79], off
	v_pk_mul_f32 v[60:61], v[60:61], v[186:187] op_sel_hi:[1,0]
	v_pk_mul_f32 v[62:63], v[62:63], v[186:187] op_sel_hi:[1,0]
	v_pk_mul_f32 v[52:53], v[52:53], v[186:187] op_sel_hi:[1,0]
	v_pk_mul_f32 v[54:55], v[54:55], v[186:187] op_sel_hi:[1,0]
	v_exp_f32_e32 v60, v60
	v_exp_f32_e32 v61, v61
	v_exp_f32_e32 v62, v62
	v_exp_f32_e32 v63, v63
	v_exp_f32_e32 v52, v52
	v_exp_f32_e32 v53, v53
	v_exp_f32_e32 v54, v54
	v_exp_f32_e32 v55, v55
	v_pk_mul_f32 v[56:57], v[56:57], v[186:187] op_sel:[0,1] op_sel_hi:[1,1]
	v_pk_mul_f32 v[58:59], v[58:59], v[186:187] op_sel:[0,1] op_sel_hi:[1,1]
	v_pk_mul_f32 v[48:49], v[48:49], v[186:187] op_sel:[0,1] op_sel_hi:[1,1]
	v_pk_mul_f32 v[50:51], v[50:51], v[186:187] op_sel:[0,1] op_sel_hi:[1,1]
	v_pk_add_f32 v[60:61], v[60:61], 1.0 op_sel_hi:[1,0]
	v_pk_add_f32 v[62:63], v[62:63], 1.0 op_sel_hi:[1,0]
	v_pk_add_f32 v[52:53], v[52:53], 1.0 op_sel_hi:[1,0]
	v_pk_add_f32 v[54:55], v[54:55], 1.0 op_sel_hi:[1,0]
	v_rcp_f32_e32 v60, v60
	v_rcp_f32_e32 v61, v61
	v_rcp_f32_e32 v62, v62
	v_rcp_f32_e32 v63, v63
	v_rcp_f32_e32 v52, v52
	v_rcp_f32_e32 v53, v53
	v_rcp_f32_e32 v54, v54
	v_rcp_f32_e32 v55, v55
	v_mad_i64_i32 v[208:209], s[4:5], v154, s68, v[220:221]
	v_lshl_add_u64 v[208:209], v[208:209], 0, v[242:243]
	v_pk_mul_f32 v[56:57], v[56:57], v[60:61]
	v_pk_mul_f32 v[58:59], v[58:59], v[62:63]
	v_pk_mul_f32 v[48:49], v[48:49], v[52:53]
	v_pk_mul_f32 v[50:51], v[50:51], v[54:55]
	v_cvt_pk_bf16_f32 v60, v56, v57
	v_cvt_pk_bf16_f32 v61, v58, v59
	v_cvt_pk_bf16_f32 v62, v48, v49
	v_cvt_pk_bf16_f32 v63, v50, v51
	global_store_dwordx4 v[208:209], v[60:63], off
	v_pk_mul_f32 v[44:45], v[44:45], v[188:189] op_sel_hi:[1,0]
	v_pk_mul_f32 v[46:47], v[46:47], v[188:189] op_sel_hi:[1,0]
	v_pk_mul_f32 v[36:37], v[36:37], v[188:189] op_sel_hi:[1,0]
	v_pk_mul_f32 v[38:39], v[38:39], v[188:189] op_sel_hi:[1,0]
	v_exp_f32_e32 v44, v44
	v_exp_f32_e32 v45, v45
	v_exp_f32_e32 v46, v46
	v_exp_f32_e32 v47, v47
	v_exp_f32_e32 v36, v36
	v_exp_f32_e32 v37, v37
	v_exp_f32_e32 v38, v38
	v_exp_f32_e32 v39, v39
	v_pk_mul_f32 v[40:41], v[40:41], v[188:189] op_sel:[0,1] op_sel_hi:[1,1]
	v_pk_mul_f32 v[42:43], v[42:43], v[188:189] op_sel:[0,1] op_sel_hi:[1,1]
; __device__ __forceinline__ unsigned cvt_pk_bf16(float lo, float hi) { unsigned r; asm volatile("v_cvt_pk_bf16_f32 %0, %1, %2" : "=v"(r) : "v"(lo), "v"(hi)); return r; }
; __device__ __forceinline__ float fast_rcp(float x) { return __builtin_amdgcn_rcpf(x); }
; #define PG8_BAR __builtin_amdgcn_s_barrier()
; __device__ __forceinline__ unsigned cvt_pk_bf16(float lo, float hi) { const f32x2 v = {lo, hi}; const bf16x2_t b = __builtin_convertvector(v, bf16x2_t); return __builtin_bit_cast(unsigned, b); }
;     __device__ __forceinline__ void operator()(const f32x4 (&acc)[2][2][4][2], const Unit& u, int wr, int wc, int fr, int fq) const {
;     ...
;             for (int m = 0; m < 4; ++m) {
;                 const int r = row0 + ai * HALF + m * 16; const float rs = rsv[ai][m], nrs = rs * -1.4426950408889634f, rs2 = rs * rs;
;                 float o[8];
; #pragma unroll
;                 for (int n = 0; n < 2; ++n) {
;                     const f32x4 t = acc[ai][0][m][n] * nrs, p = (acc[ai][0][m][n] * acc[ai][1][m][n]) * rs2;
; #pragma unroll
;                     for (int j = 0; j < 4; ++j) o[4 * n + j] = p[j] * fast_rcp(1.0f + __builtin_amdgcn_exp2f(t[j]));
;                 }
;                 u32x4 w; w.x = cvt_pk_bf16(o[0], o[1]); w.y = cvt_pk_bf16(o[2], o[3]); w.z = cvt_pk_bf16(o[4], o[5]); w.w = cvt_pk_bf16(o[6], o[7]);
;                 *(u32x4*)(O + (size_t)r * ldo + col0) = w;
; template <class Epi, class Sched, bool ALIGN_EPI = false, bool SP2 = false>
; __device__ __forceinline__ void gemm_phase(PG8_LAS unsigned char* lds, const Gemm g, const Sched& S, const Epi& E) {
;     ...
;         if (!has_next) break;
; #pragma unroll
;         for (int a = 0; a < 2; ++a)
; #pragma unroll
;             for (int b = 0; b < 2; ++b)
; #pragma unroll
;                 for (int m = 0; m < 4; ++m)
; #pragma unroll
;                     for (int n = 0; n < 2; ++n) acc[a][b][m][n] = (f32x4){0.f, 0.f, 0.f, 0.f};
;         cur = nxt; cA = nA; cB = nB; ++ui;
;         if constexpr (ALIGN_EPI) { if (wr == 1) PG8_BAR; }
	v_pk_mul_f32 v[32:33], v[32:33], v[188:189] op_sel:[0,1] op_sel_hi:[1,1]
	v_pk_mul_f32 v[34:35], v[34:35], v[188:189] op_sel:[0,1] op_sel_hi:[1,1]
	v_pk_add_f32 v[44:45], v[44:45], 1.0 op_sel_hi:[1,0]
	v_pk_add_f32 v[46:47], v[46:47], 1.0 op_sel_hi:[1,0]
	v_pk_add_f32 v[36:37], v[36:37], 1.0 op_sel_hi:[1,0]
	v_pk_add_f32 v[38:39], v[38:39], 1.0 op_sel_hi:[1,0]
	v_rcp_f32_e32 v44, v44
	v_rcp_f32_e32 v45, v45
	v_rcp_f32_e32 v46, v46
	v_rcp_f32_e32 v47, v47
	v_rcp_f32_e32 v36, v36
	v_rcp_f32_e32 v37, v37
	v_rcp_f32_e32 v38, v38
	v_rcp_f32_e32 v39, v39
	v_mad_i64_i32 v[208:209], s[4:5], v152, s68, v[220:221]
	v_lshl_add_u64 v[208:209], v[208:209], 0, v[242:243]
	v_pk_mul_f32 v[40:41], v[40:41], v[44:45]
	v_pk_mul_f32 v[42:43], v[42:43], v[46:47]
	v_pk_mul_f32 v[32:33], v[32:33], v[36:37]
	v_pk_mul_f32 v[34:35], v[34:35], v[38:39]
	v_cvt_pk_bf16_f32 v44, v40, v41
	v_cvt_pk_bf16_f32 v45, v42, v43
	v_cvt_pk_bf16_f32 v46, v32, v33
	v_cvt_pk_bf16_f32 v47, v34, v35
	global_store_dwordx4 v[208:209], v[44:47], off
	v_pk_mul_f32 v[28:29], v[28:29], v[190:191] op_sel_hi:[1,0]
	v_pk_mul_f32 v[30:31], v[30:31], v[190:191] op_sel_hi:[1,0]
	v_pk_mul_f32 v[20:21], v[20:21], v[190:191] op_sel_hi:[1,0]
	v_pk_mul_f32 v[22:23], v[22:23], v[190:191] op_sel_hi:[1,0]
	v_exp_f32_e32 v28, v28
	v_exp_f32_e32 v29, v29
	v_exp_f32_e32 v30, v30
	v_exp_f32_e32 v31, v31
	v_exp_f32_e32 v20, v20
	v_exp_f32_e32 v21, v21
	v_exp_f32_e32 v22, v22
	v_exp_f32_e32 v23, v23
	v_pk_mul_f32 v[24:25], v[24:25], v[190:191] op_sel:[0,1] op_sel_hi:[1,1]
	v_pk_mul_f32 v[26:27], v[26:27], v[190:191] op_sel:[0,1] op_sel_hi:[1,1]
	v_pk_mul_f32 v[16:17], v[16:17], v[190:191] op_sel:[0,1] op_sel_hi:[1,1]
	v_pk_mul_f32 v[18:19], v[18:19], v[190:191] op_sel:[0,1] op_sel_hi:[1,1]
	v_pk_add_f32 v[28:29], v[28:29], 1.0 op_sel_hi:[1,0]
	v_pk_add_f32 v[30:31], v[30:31], 1.0 op_sel_hi:[1,0]
	v_pk_add_f32 v[20:21], v[20:21], 1.0 op_sel_hi:[1,0]
	v_pk_add_f32 v[22:23], v[22:23], 1.0 op_sel_hi:[1,0]
	v_rcp_f32_e32 v28, v28
	v_rcp_f32_e32 v29, v29
	v_rcp_f32_e32 v30, v30
	v_rcp_f32_e32 v31, v31
	v_rcp_f32_e32 v20, v20
	v_rcp_f32_e32 v21, v21
	v_rcp_f32_e32 v22, v22
	v_rcp_f32_e32 v23, v23
	v_mad_i64_i32 v[208:209], s[4:5], v150, s68, v[220:221]
	v_lshl_add_u64 v[208:209], v[208:209], 0, v[242:243]
	v_pk_mul_f32 v[24:25], v[24:25], v[28:29]
	v_pk_mul_f32 v[26:27], v[26:27], v[30:31]
	v_pk_mul_f32 v[16:17], v[16:17], v[20:21]
	v_pk_mul_f32 v[18:19], v[18:19], v[22:23]
	v_cvt_pk_bf16_f32 v28, v24, v25
	v_cvt_pk_bf16_f32 v29, v26, v27
	v_cvt_pk_bf16_f32 v30, v16, v17
	v_cvt_pk_bf16_f32 v31, v18, v19
	global_store_dwordx4 v[208:209], v[28:31], off
	v_pk_mul_f32 v[12:13], v[12:13], v[204:205] op_sel_hi:[1,0]
	v_pk_mul_f32 v[14:15], v[14:15], v[204:205] op_sel_hi:[1,0]
	v_pk_mul_f32 v[4:5], v[4:5], v[204:205] op_sel_hi:[1,0]
	v_pk_mul_f32 v[6:7], v[6:7], v[204:205] op_sel_hi:[1,0]
	v_exp_f32_e32 v12, v12
	v_exp_f32_e32 v13, v13
	v_exp_f32_e32 v14, v14
	v_exp_f32_e32 v15, v15
	v_exp_f32_e32 v4, v4
	v_exp_f32_e32 v5, v5
	v_exp_f32_e32 v6, v6
	v_exp_f32_e32 v7, v7
	v_pk_mul_f32 v[8:9], v[8:9], v[204:205] op_sel:[0,1] op_sel_hi:[1,1]
	v_pk_mul_f32 v[10:11], v[10:11], v[204:205] op_sel:[0,1] op_sel_hi:[1,1]
	v_pk_mul_f32 v[0:1], v[0:1], v[204:205] op_sel:[0,1] op_sel_hi:[1,1]
	v_pk_mul_f32 v[2:3], v[2:3], v[204:205] op_sel:[0,1] op_sel_hi:[1,1]
	v_pk_add_f32 v[12:13], v[12:13], 1.0 op_sel_hi:[1,0]
	v_pk_add_f32 v[14:15], v[14:15], 1.0 op_sel_hi:[1,0]
	v_pk_add_f32 v[4:5], v[4:5], 1.0 op_sel_hi:[1,0]
	v_pk_add_f32 v[6:7], v[6:7], 1.0 op_sel_hi:[1,0]
	v_rcp_f32_e32 v12, v12
	v_rcp_f32_e32 v13, v13
	v_rcp_f32_e32 v14, v14
	v_rcp_f32_e32 v15, v15
	v_rcp_f32_e32 v4, v4
	v_rcp_f32_e32 v5, v5
	v_rcp_f32_e32 v6, v6
	v_rcp_f32_e32 v7, v7
	v_mad_i64_i32 v[208:209], s[4:5], v148, s68, v[220:221]
	v_lshl_add_u64 v[208:209], v[208:209], 0, v[242:243]
	v_pk_mul_f32 v[8:9], v[8:9], v[12:13]
	v_pk_mul_f32 v[10:11], v[10:11], v[14:15]
	v_pk_mul_f32 v[0:1], v[0:1], v[4:5]
	v_pk_mul_f32 v[2:3], v[2:3], v[6:7]
	v_cvt_pk_bf16_f32 v12, v8, v9
	v_cvt_pk_bf16_f32 v13, v10, v11
	v_cvt_pk_bf16_f32 v14, v0, v1
	v_cvt_pk_bf16_f32 v15, v2, v3
	global_store_dwordx4 v[208:209], v[12:15], off
	s_cbranch_vccnz .LBB0_255
	s_andn2_b64 vcc, exec, s[16:17]
	s_cbranch_vccnz .LBB0_254
	s_barrier
	s_branch .LBB0_254

; #define PG8_BAR __builtin_amdgcn_s_barrier()
; template <class Epi, class Sched, bool ALIGN_EPI = false, bool SP2 = false>
; __device__ __forceinline__ void gemm_phase(PG8_LAS unsigned char* lds, const Gemm g, const Sched& S, const Epi& E) {
;     int tid_ = threadIdx.x; asm volatile("" : "+v"(tid_));
;     const int tid = tid_, wid = __builtin_amdgcn_readfirstlane(tid >> 6), lane = tid & 63, wr = wid >> 2, wc = wid & 3, fr = lane & 15, fq = lane >> 4;
;     int K_ = g.K; asm volatile("" : "+s"(K_));
;     const int K = K_, nt = K / BK;
;     unsigned voffA[2], voffB[2];
; #pragma unroll
;     for (int i = 0; i < 2; ++i) { int R, C; stage_rc(tid * 16 + i * 8192, R, C); const int Rb = Epi::PERM ? ((R & ~31) + perm32(R & 31)) : R;
;         voffA[i] = (unsigned)(R * K + C) * 2u; voffB[i] = (unsigned)(Rb * K + C) * 2u; }
;     const size_t kstep = (size_t)(BK * 2);
;     const size_t hstep = (size_t)HALF * K * 2;
;     const size_t tstep = 2 * hstep;
;     const unsigned ldsw = (unsigned)wid * 1024u;
;     const int aoff = lds_byte(wr * 64 + fr, fq * 8), boff = lds_byte(wc * 32 + fr, fq * 8);
;     ...
;     Unit cur, nxt; int ui = 0;
;     if (!S.next(0, cur)) return;
;     f32x4 acc[2][2][4][2];
; #pragma unroll
;     for (int a = 0; a < 2; ++a)
; #pragma unroll
;         for (int b = 0; b < 2; ++b)
; #pragma unroll
;             for (int m = 0; m < 4; ++m)
; #pragma unroll
;                 for (int n = 0; n < 2; ++n) acc[a][b][m][n] = (f32x4){0.f, 0.f, 0.f, 0.f};
;     bf16x8 At[4][2], B0[2][2], B1[2][2];
;     const char* cA = (const char*)g.A + (size_t)cur.pm * tstep; const char* cB = (const char*)g.Bt + (size_t)cur.pn * tstep;
;     S.a_ready(cur);
;     if constexpr (SP2) {
;         PG8_STAGE(PG8_SB(0, 0), cB, voffB); PG8_STAGE(PG8_SB(0, 1), cB + hstep, voffB); PG8_STAGE(PG8_SA(0, 0), cA, voffA); PG8_STAGE(PG8_SA(0, 1), cA + hstep, voffA);
;         if (wr == 1) PG8_BAR;
;         PG8_WAIT_V(2); PG8_BAR;
;         PG8_STAGE(PG8_SB(1, 0), cB + kstep, voffB); PG8_STAGE(PG8_SA(1, 0), cA + kstep, voffA); PG8_STAGE(PG8_SB(1, 1), cB + hstep + kstep, voffB);
;         PG8_WAIT_V(6); PG8_BAR;
;     } else {
;         PG8_STAGE(PG8_SB(0, 0), cB, voffB); PG8_STAGE(PG8_SA(0, 0), cA, voffA); PG8_STAGE(PG8_SB(0, 1), cB + hstep, voffB); PG8_STAGE(PG8_SA(0, 1), cA + hstep, voffA);
;         if (wr == 1) PG8_BAR;
;         PG8_WAIT_V(4); PG8_BAR;
.LBB0_999:
	s_cmp_lt_i32 s28, 7
	s_cselect_b64 s[4:5], -1, 0
	s_and_b64 s[8:9], s[4:5], s[0:1]
	s_andn2_b64 vcc, exec, s[8:9]
	s_cbranch_vccnz .LBB0_1041
	v_lshlrev_b32_e32 v236, 4, v192
	v_mov_b32_e32 v237, 0
	v_lshl_add_u64 v[236:237], s[44:45], 0, v[236:237]
	v_mov_b32_e32 v12, v192
	s_movk_i32 s0, 0x400
	v_readfirstlane_b32 s7, v12
	s_cmpk_gt_i32 s2, 0x5d7
	s_cbranch_scc1 .LBB0_1021
	v_lshlrev_b32_e32 v0, 4, v12
	v_add_u32_e32 v1, 0x2000, v0
	s_waitcnt lgkmcnt(0)
	v_ashrrev_i32_e32 v2, 31, v1
	v_lshrrev_b32_e32 v2, 22, v2
	v_add_u32_e32 v2, v1, v2
	v_ashrrev_i32_e32 v2, 10, v2
	v_mul_i32_i24_e32 v3, 0x400, v2
	v_sub_u32_e32 v1, v1, v3
	v_lshrrev_b32_e32 v3, 4, v1
	v_bitop3_b32 v1, v3, v1, 32 bitop3:0x6c
	v_ashrrev_i32_e32 v3, 31, v1
	v_lshrrev_b32_e32 v3, 26, v3
	v_add_u32_e32 v3, v1, v3
	v_lshlrev_b32_e32 v5, 3, v2
	v_ashrrev_i32_e32 v4, 6, v3
	v_and_b32_e32 v5, -16, v5
	v_lshlrev_b32_e32 v2, 5, v2
	v_add_u32_e32 v5, v4, v5
	v_and_b32_e32 v13, 32, v2
	v_and_b32_e32 v2, 0xc0, v3
	v_and_b32_e32 v4, 3, v4
	s_mov_b32 s4, 0x7fffffe0
	v_lshrrev_b32_e32 v6, 2, v5
	v_lshlrev_b32_e32 v7, 1, v5
	v_sub_u32_e32 v1, v1, v2
	v_mov_b32_e32 v2, 1
	v_and_or_b32 v4, v5, s4, v4
	v_and_b32_e32 v6, 4, v6
	v_and_b32_e32 v7, 24, v7
	v_ashrrev_i16_sdwa v1, v2, sext(v1) dst_sel:DWORD dst_unused:UNUSED_PAD src0_sel:DWORD src1_sel:BYTE_0
	v_or3_b32 v4, v4, v6, v7
	v_bfe_i32 v14, v1, 0, 16
	v_mul_lo_u32 v4, v4, s0
	v_add_u32_e32 v1, v13, v14
	v_mul_lo_u32 v15, v5, s0
	v_add_lshl_u32 v128, v4, v1, 1
	v_add_lshl_u32 v130, v1, v15, 1
	v_bfe_i32 v1, v12, 27, 1
	v_lshrrev_b32_e32 v1, 22, v1
	v_add_u32_e32 v1, v0, v1
	v_and_b32_e32 v1, 0xfffffc00, v1
	v_sub_u32_e32 v0, v0, v1
	v_lshrrev_b32_e32 v1, 4, v0
	v_ashrrev_i32_e32 v4, 31, v12
	v_bitop3_b32 v0, v1, v0, 32 bitop3:0x6c
	v_lshrrev_b32_e32 v4, 26, v4
	v_ashrrev_i32_e32 v1, 31, v0
	v_add_u32_e32 v4, v12, v4
	v_lshrrev_b32_e32 v1, 26, v1
	v_ashrrev_i32_e32 v4, 6, v4
	v_add_u32_e32 v1, v0, v1
	v_lshlrev_b32_e32 v5, 3, v4
	s_add_u32 s3, s26, 0x1600000
	v_ashrrev_i32_e32 v3, 6, v1
	v_and_b32_e32 v5, -16, v5
	s_addc_u32 s40, s27, 0
	v_add_u32_e32 v5, v3, v5
	v_and_b32_e32 v3, 3, v3
	s_ashr_i32 s42, s2, 31
	v_and_or_b32 v3, v5, s4, v3
	s_lshr_b32 s4, s42, 29
	s_add_i32 s4, s2, s4
	s_ashr_i32 s18, s7, 6
	s_ashr_i32 s1, s0, 31
	s_ashr_i32 s5, s4, 3
	s_and_b32 s4, s4, -8
	s_ashr_i32 s19, s7, 8
	s_lshl_b64 s[10:11], s[0:1], 8
	s_lshl_b64 s[12:13], s[0:1], 9
	s_lshl_b32 s41, s18, 10
	s_sub_i32 s4, s2, s4
	s_cmp_lt_i32 s4, 0
	s_movk_i32 s43, 0xbc
	s_cselect_b32 s6, s43, 0xbb
	s_mul_i32 s4, s4, s6
	s_add_i32 s4, s4, s5
	s_mul_hi_i32 s5, s4, 0x2e8ba2e9
	s_lshr_b32 s6, s5, 31
	s_ashr_i32 s5, s5, 5
	v_and_b32_e32 v1, 0xc0, v1
	s_add_i32 s5, s5, s6
	v_lshrrev_b32_e32 v6, 2, v5
	v_lshlrev_b32_e32 v7, 1, v5
	v_sub_u32_e32 v0, v0, v1
	s_lshl_b32 s14, s5, 3
	v_and_b32_e32 v6, 4, v6
	v_and_b32_e32 v7, 24, v7
	v_lshlrev_b32_e32 v4, 5, v4
	v_ashrrev_i16_sdwa v0, v2, sext(v0) dst_sel:DWORD dst_unused:UNUSED_PAD src0_sel:DWORD src1_sel:BYTE_0
	s_sub_i32 s6, 0x44, s14
	s_mulk_i32 s5, 0xb0
	v_or3_b32 v3, v3, v6, v7
	v_and_b32_e32 v16, 32, v4
	v_bfe_i32 v17, v0, 0, 16
	s_min_u32 s15, s6, 8
	s_sub_i32 s16, s4, s5
	v_mul_lo_u32 v3, v3, s0
	v_add_u32_e32 v0, v16, v17
	s_sext_i32_i16 s4, s16
	v_cvt_f32_ubyte0_e32 v2, s15
	v_add_lshl_u32 v132, v3, v0, 1
	v_cvt_f32_i32_e32 v1, s4
	v_rcp_iflag_f32_e32 v3, v2
	v_mul_lo_u32 v18, v5, s0
	v_add_lshl_u32 v134, v0, v18, 1
	s_ashr_i32 s4, s4, 30
	v_mul_f32_e32 v0, v1, v3
	v_trunc_f32_e32 v0, v0
	v_fma_f32 v1, -v0, v2, v1
	v_cvt_i32_f32_e32 v0, v0
	s_or_b32 s6, s4, 1
	v_cmp_ge_f32_e64 s[4:5], |v1|, v2
	s_and_b64 s[4:5], s[4:5], exec
	s_cselect_b32 s4, s6, 0
	v_readfirstlane_b32 s5, v0
	s_add_i32 s6, s5, s4
	s_mul_i32 s4, s6, s15
	s_sub_i32 s4, s16, s4
	s_sext_i32_i16 s4, s4
	s_add_i32 s4, s14, s4
	s_ashr_i32 s5, s4, 31
	s_mul_i32 s5, s12, s5
	s_mul_hi_u32 s14, s12, s4
	s_add_i32 s5, s14, s5
	s_lshr_b64 s[14:15], s[0:1], 23
	s_mul_i32 s15, s14, s4
	s_bfe_i64 s[16:17], s[6:7], 0x100000
	s_add_i32 s5, s5, s15
	s_mul_i32 s15, s12, s17
	s_mul_hi_u32 s17, s12, s16
	s_add_i32 s15, s17, s15
	s_mul_i32 s14, s14, s16
	s_add_i32 s15, s15, s14
	s_mul_i32 s14, s12, s16
	s_add_u32 s38, s3, s14
	s_addc_u32 s39, s40, s15
	s_add_i32 s48, s41, 0
	s_add_i32 m0, s48, 0x10000
	s_mul_i32 s20, s12, s4
	global_load_lds_dwordx4 v132, s[38:39]
	s_add_i32 m0, s48, 0x12000
	s_add_u32 s14, s38, s10
	global_load_lds_dwordx4 v128, s[38:39]
	s_addc_u32 s15, s39, s11
	s_add_i32 m0, s48, 0x14000
	v_mov_b32_e32 v133, 0
	global_load_lds_dwordx4 v132, s[14:15]
	s_add_i32 m0, s48, 0x16000
	s_add_u32 s36, s34, s20
	s_addc_u32 s37, s35, s5
	s_add_i32 s49, s48, 0x2000
	global_load_lds_dwordx4 v128, s[14:15]
	s_mov_b32 m0, s48
	s_add_u32 s16, s36, s10
	global_load_lds_dwordx4 v134, s[36:37]
	s_mov_b32 m0, s49
	s_addc_u32 s17, s37, s11
	s_add_i32 s56, s48, 0x4000
	global_load_lds_dwordx4 v130, s[36:37]
	s_mov_b32 m0, s56
	s_add_i32 s57, s48, 0x6000
	global_load_lds_dwordx4 v134, s[16:17]
	s_mov_b32 m0, s57
	v_mov_b32_e32 v129, v133
	global_load_lds_dwordx4 v130, s[16:17]
	v_mov_b32_e32 v135, v133
	v_mov_b32_e32 v131, v133
	s_cmp_eq_u32 s19, 1
	s_mov_b32 s58, 0
	v_lshl_add_u64 v[8:9], s[38:39], 0, v[132:133]
	v_lshl_add_u64 v[4:5], s[38:39], 0, v[128:129]
	v_lshl_add_u64 v[2:3], s[14:15], 0, v[132:133]
	v_lshl_add_u64 v[0:1], s[14:15], 0, v[128:129]
	v_lshl_add_u64 v[6:7], s[36:37], 0, v[134:135]
	s_cselect_b64 s[14:15], -1, 0
	s_cmp_lg_u32 s19, 1
	v_lshl_add_u64 v[10:11], s[36:37], 0, v[130:131]
	s_cbranch_scc1 .LBB0_1003
	s_barrier

; #define PG8_STAGE(bufoff, gbase, voff) do { _Pragma("unroll") for (int _i = 0; _i < 2; ++_i) \
;         __builtin_amdgcn_global_load_lds((const unsigned*)((const char*)(gbase) + (voff)[_i]), (PG8_LAS unsigned*)(lds + (bufoff) + ldsw + _i * 8192), 16, 0, 0); } while (0)
; #define PG8_LDA(dst, b, h) do { _Pragma("unroll") for (int m = 0; m < 4; ++m) _Pragma("unroll") for (int k = 0; k < 2; ++k) dst[m][k] = *(const PG8_LAS bf16x8*)(lds + PG8_SA(b, h) + aoff + m * 2048 + k * 1024); } while (0)
; #define PG8_LDB(dst, b, h) do { _Pragma("unroll") for (int n = 0; n < 2; ++n) _Pragma("unroll") for (int k = 0; k < 2; ++k) dst[n][k] = *(const PG8_LAS bf16x8*)(lds + PG8_SB(b, h) + boff + n * 2048 + k * 1024); } while (0)
; #define PG8_MMA(ai, bj, At, Bt) do { __builtin_amdgcn_s_setprio(1); _Pragma("unroll") for (int m = 0; m < 4; ++m) _Pragma("unroll") for (int n = 0; n < 2; ++n) _Pragma("unroll") for (int k = 0; k < 2; ++k) \
;         acc[ai][bj][m][n] = __builtin_amdgcn_mfma_f32_16x16x32_bf16(Bt[n][k], At[m][k], acc[ai][bj][m][n], 0, 0, 0); __builtin_amdgcn_s_setprio(0); } while (0)
; #define PG8_WAIT_V(n) asm volatile("s_waitcnt vmcnt(" #n ")" ::: "memory")
; #define PG8_WAIT_L(n) asm volatile("s_waitcnt lgkmcnt(" #n ")" ::: "memory")
; #define PG8_BAR __builtin_amdgcn_s_barrier()
; #define PG8_SCHED __builtin_amdgcn_sched_barrier(0)
; template <class Epi, class Sched, bool ALIGN_EPI = false, bool SP2 = false>
; __device__ __forceinline__ void gemm_phase(PG8_LAS unsigned char* lds, const Gemm g, const Sched& S, const Epi& E) {
;     ...
;             PG8_LDB(B0, 0, 0); PG8_LDB(B1, 0, 1); PG8_SCHED; PG8_LDA(At, 0, 0); PG8_STAGE(PG8_SA(1, 1), a1 + hstep, voffA);
;             PG8_WAIT_V(8); PG8_WAIT_L(0); PG8_BAR; PG8_MMA(0, 0, At, B0); PG8_MMA(0, 1, At, B1); PG8_BAR; PG8_SCHED;
;             PG8_LDA(At, 0, 1); PG8_STAGE(PG8_SB(0, 0), b2, voffB); PG8_STAGE(PG8_SB(0, 1), b2 + hstep, voffB); PG8_STAGE(PG8_SA(0, 0), a2, voffA);
.LBB0_1014:
	ds_read_b128 v[146:149], v167
	ds_read_b128 v[150:153], v167 offset:1024
	ds_read_b128 v[154:157], v167 offset:2048
	ds_read_b128 v[158:161], v167 offset:3072
	ds_read_b128 v[172:175], v168
	ds_read_b128 v[176:179], v168 offset:1024
	ds_read_b128 v[180:183], v168 offset:2048
	ds_read_b128 v[184:187], v168 offset:3072
	s_add_i32 s71, s38, 2
	s_add_u32 s72, s36, 0x80
	s_addc_u32 s39, s37, 0
	s_cmp_eq_u32 s62, s38
	s_cselect_b32 s38, s6, s72
	s_cselect_b32 s39, s7, s39
	s_cselect_b32 s73, s23, s70
	s_cselect_b32 s72, s22, s33
	v_lshl_add_u64 v[162:163], s[36:37], 0, v[138:139]
	s_add_i32 m0, s48, 0xc000
	ds_read_b128 v[188:191], v169
	ds_read_b128 v[194:197], v169 offset:1024
	ds_read_b128 v[198:201], v169 offset:2048
	ds_read_b128 v[202:205], v169 offset:3072
	ds_read_b128 v[206:209], v169 offset:4096
	ds_read_b128 v[210:213], v169 offset:5120
	ds_read_b128 v[214:217], v169 offset:6144
	ds_read_b128 v[218:221], v169 offset:7168
	global_load_lds_dwordx4 v[162:163], off
	v_lshl_add_u64 v[162:163], s[36:37], 0, v[140:141]
	s_add_i32 m0, s48, 0xe000
	s_nop 0
	global_load_lds_dwordx4 v[162:163], off
	s_waitcnt vmcnt(8)
	s_waitcnt lgkmcnt(0)
	s_barrier
	s_setprio 1
	s_waitcnt lgkmcnt(0)
	v_mfma_f32_16x16x32_bf16 v[120:123], v[146:149], v[188:191], v[120:123]
	v_mfma_f32_16x16x32_bf16 v[116:119], v[154:157], v[188:191], v[116:119]
	v_mfma_f32_16x16x32_bf16 v[108:111], v[146:149], v[198:201], v[108:111]
	v_mfma_f32_16x16x32_bf16 v[100:103], v[154:157], v[198:201], v[100:103]
	v_mfma_f32_16x16x32_bf16 v[92:95], v[146:149], v[206:209], v[92:95]
	v_mfma_f32_16x16x32_bf16 v[84:87], v[154:157], v[206:209], v[84:87]
	v_mfma_f32_16x16x32_bf16 v[76:79], v[146:149], v[214:217], v[76:79]
	v_mfma_f32_16x16x32_bf16 v[68:71], v[154:157], v[214:217], v[68:71]
	v_mfma_f32_16x16x32_bf16 v[120:123], v[150:153], v[194:197], v[120:123]
	v_mfma_f32_16x16x32_bf16 v[116:119], v[158:161], v[194:197], v[116:119]
	v_mfma_f32_16x16x32_bf16 v[108:111], v[150:153], v[202:205], v[108:111]
	v_mfma_f32_16x16x32_bf16 v[100:103], v[158:161], v[202:205], v[100:103]
	v_mfma_f32_16x16x32_bf16 v[92:95], v[150:153], v[210:213], v[92:95]
	v_mfma_f32_16x16x32_bf16 v[84:87], v[158:161], v[210:213], v[84:87]
	v_mfma_f32_16x16x32_bf16 v[76:79], v[150:153], v[218:221], v[76:79]
	v_mfma_f32_16x16x32_bf16 v[68:71], v[158:161], v[218:221], v[68:71]
	s_setprio 0
	s_setprio 1
	v_mfma_f32_16x16x32_bf16 v[124:127], v[172:175], v[188:191], v[124:127]
	v_mfma_f32_16x16x32_bf16 v[112:115], v[180:183], v[188:191], v[112:115]
	v_mfma_f32_16x16x32_bf16 v[104:107], v[172:175], v[198:201], v[104:107]
	v_mfma_f32_16x16x32_bf16 v[96:99], v[180:183], v[198:201], v[96:99]
	v_mfma_f32_16x16x32_bf16 v[88:91], v[172:175], v[206:209], v[88:91]
	v_mfma_f32_16x16x32_bf16 v[80:83], v[180:183], v[206:209], v[80:83]
	v_mfma_f32_16x16x32_bf16 v[72:75], v[172:175], v[214:217], v[72:75]
	v_mfma_f32_16x16x32_bf16 v[64:67], v[180:183], v[214:217], v[64:67]
	v_mfma_f32_16x16x32_bf16 v[124:127], v[176:179], v[194:197], v[124:127]
	v_mfma_f32_16x16x32_bf16 v[112:115], v[184:187], v[194:197], v[112:115]
	v_mfma_f32_16x16x32_bf16 v[104:107], v[176:179], v[202:205], v[104:107]
	v_mfma_f32_16x16x32_bf16 v[96:99], v[184:187], v[202:205], v[96:99]
	v_mfma_f32_16x16x32_bf16 v[88:91], v[176:179], v[210:213], v[88:91]
	v_mfma_f32_16x16x32_bf16 v[80:83], v[184:187], v[210:213], v[80:83]
	v_mfma_f32_16x16x32_bf16 v[72:75], v[176:179], v[218:221], v[72:75]
	v_mfma_f32_16x16x32_bf16 v[64:67], v[184:187], v[218:221], v[64:67]
	s_setprio 0
	s_barrier
	s_add_i32 s74, s65, s41
	v_lshl_add_u64 v[162:163], s[72:73], 0, v[132:133]
	s_mov_b32 m0, s74
	ds_read_b128 v[188:191], v169 offset:16384
	ds_read_b128 v[194:197], v169 offset:17408
	ds_read_b128 v[198:201], v169 offset:18432
	ds_read_b128 v[202:205], v169 offset:19456
	ds_read_b128 v[206:209], v169 offset:20480
	ds_read_b128 v[210:213], v169 offset:21504
	ds_read_b128 v[214:217], v169 offset:22528
	ds_read_b128 v[218:221], v169 offset:23552
	global_load_lds_dwordx4 v[162:163], off
	s_add_i32 m0, s74, 0x2000
	v_lshl_add_u64 v[222:223], s[72:73], 0, v[128:129]
	s_add_u32 s72, s72, s10
	s_addc_u32 s73, s73, s11
	s_add_i32 s74, s66, s41
	global_load_lds_dwordx4 v[222:223], off
	v_lshl_add_u64 v[224:225], s[72:73], 0, v[132:133]
	s_mov_b32 m0, s74
	v_lshl_add_u64 v[226:227], s[72:73], 0, v[128:129]
	global_load_lds_dwordx4 v[224:225], off
	s_add_i32 m0, s74, 0x2000
	v_lshl_add_u64 v[228:229], s[38:39], 0, v[134:135]
	global_load_lds_dwordx4 v[226:227], off
	s_mov_b32 m0, s48
	v_lshl_add_u64 v[230:231], s[38:39], 0, v[130:131]
	global_load_lds_dwordx4 v[228:229], off
	s_mov_b32 m0, s49
	s_nop 0
	global_load_lds_dwordx4 v[230:231], off
	s_cmp_lg_u32 s71, 2
	s_cbranch_scc1 .Lss_p6_skip
	s_lshl_b32 s84, s4, 14
	s_mov_b32 s85, 0
	s_add_i32 m0, s48, 0x20000
	v_lshl_add_u64 v[238:239], v[236:237], 0, s[84:85]
	s_add_u32 s84, s84, 0x2000
	global_load_lds_dwordx4 v[238:239], off
	s_add_i32 m0, s48, 0x22000
	v_lshl_add_u64 v[238:239], v[236:237], 0, s[84:85]
	global_load_lds_dwordx4 v[238:239], off
; #define PG8_STAGE(bufoff, gbase, voff) do { _Pragma("unroll") for (int _i = 0; _i < 2; ++_i) \
;         __builtin_amdgcn_global_load_lds((const unsigned*)((const char*)(gbase) + (voff)[_i]), (PG8_LAS unsigned*)(lds + (bufoff) + ldsw + _i * 8192), 16, 0, 0); } while (0)
; #define PG8_LDA(dst, b, h) do { _Pragma("unroll") for (int m = 0; m < 4; ++m) _Pragma("unroll") for (int k = 0; k < 2; ++k) dst[m][k] = *(const PG8_LAS bf16x8*)(lds + PG8_SA(b, h) + aoff + m * 2048 + k * 1024); } while (0)
; #define PG8_LDB(dst, b, h) do { _Pragma("unroll") for (int n = 0; n < 2; ++n) _Pragma("unroll") for (int k = 0; k < 2; ++k) dst[n][k] = *(const PG8_LAS bf16x8*)(lds + PG8_SB(b, h) + boff + n * 2048 + k * 1024); } while (0)
; #define PG8_MMA(ai, bj, At, Bt) do { __builtin_amdgcn_s_setprio(1); _Pragma("unroll") for (int m = 0; m < 4; ++m) _Pragma("unroll") for (int n = 0; n < 2; ++n) _Pragma("unroll") for (int k = 0; k < 2; ++k) \
;         acc[ai][bj][m][n] = __builtin_amdgcn_mfma_f32_16x16x32_bf16(Bt[n][k], At[m][k], acc[ai][bj][m][n], 0, 0, 0); __builtin_amdgcn_s_setprio(0); } while (0)
; #define PG8_WAIT_V(n) asm volatile("s_waitcnt vmcnt(" #n ")" ::: "memory")
; #define PG8_WAIT_L(n) asm volatile("s_waitcnt lgkmcnt(" #n ")" ::: "memory")
; #define PG8_BAR __builtin_amdgcn_s_barrier()
; #define PG8_SCHED __builtin_amdgcn_sched_barrier(0)
; template <class Epi, class Sched, bool ALIGN_EPI = false, bool SP2 = false>
; __device__ __forceinline__ void gemm_phase(PG8_LAS unsigned char* lds, const Gemm g, const Sched& S, const Epi& E) {
;     ...
;             PG8_WAIT_V(8); PG8_WAIT_L(0); PG8_BAR; PG8_MMA(1, 0, At, B0); PG8_MMA(1, 1, At, B1); PG8_BAR; PG8_SCHED;
;             PG8_LDB(B0, 1, 0); PG8_LDB(B1, 1, 1); PG8_SCHED; PG8_LDA(At, 1, 0); PG8_STAGE(PG8_SA(0, 1), a2 + hstep, voffA);
;             PG8_WAIT_V(8); PG8_WAIT_L(0); PG8_BAR; PG8_MMA(0, 0, At, B0); PG8_MMA(0, 1, At, B1); PG8_BAR; PG8_SCHED;
.Lss_p6_skip:
	s_waitcnt vmcnt(8)
	s_waitcnt lgkmcnt(0)
	s_barrier
	s_setprio 1
	s_waitcnt lgkmcnt(0)
	v_mfma_f32_16x16x32_bf16 v[60:63], v[146:149], v[188:191], v[60:63]
	v_mfma_f32_16x16x32_bf16 v[52:55], v[154:157], v[188:191], v[52:55]
	v_mfma_f32_16x16x32_bf16 v[44:47], v[146:149], v[198:201], v[44:47]
	v_mfma_f32_16x16x32_bf16 v[36:39], v[154:157], v[198:201], v[36:39]
	v_mfma_f32_16x16x32_bf16 v[28:31], v[146:149], v[206:209], v[28:31]
	v_mfma_f32_16x16x32_bf16 v[20:23], v[154:157], v[206:209], v[20:23]
	v_mfma_f32_16x16x32_bf16 v[12:15], v[146:149], v[214:217], v[12:15]
	v_mfma_f32_16x16x32_bf16 v[4:7], v[154:157], v[214:217], v[4:7]
	v_mfma_f32_16x16x32_bf16 v[60:63], v[150:153], v[194:197], v[60:63]
	v_mfma_f32_16x16x32_bf16 v[52:55], v[158:161], v[194:197], v[52:55]
	v_mfma_f32_16x16x32_bf16 v[44:47], v[150:153], v[202:205], v[44:47]
	v_mfma_f32_16x16x32_bf16 v[36:39], v[158:161], v[202:205], v[36:39]
	v_mfma_f32_16x16x32_bf16 v[28:31], v[150:153], v[210:213], v[28:31]
	v_mfma_f32_16x16x32_bf16 v[20:23], v[158:161], v[210:213], v[20:23]
	v_mfma_f32_16x16x32_bf16 v[12:15], v[150:153], v[218:221], v[12:15]
	v_mfma_f32_16x16x32_bf16 v[4:7], v[158:161], v[218:221], v[4:7]
	s_setprio 0
	s_setprio 1
	v_mfma_f32_16x16x32_bf16 v[56:59], v[172:175], v[188:191], v[56:59]
	v_mfma_f32_16x16x32_bf16 v[48:51], v[180:183], v[188:191], v[48:51]
	v_mfma_f32_16x16x32_bf16 v[40:43], v[172:175], v[198:201], v[40:43]
	v_mfma_f32_16x16x32_bf16 v[32:35], v[180:183], v[198:201], v[32:35]
	v_mfma_f32_16x16x32_bf16 v[24:27], v[172:175], v[206:209], v[24:27]
	v_mfma_f32_16x16x32_bf16 v[16:19], v[180:183], v[206:209], v[16:19]
	v_mfma_f32_16x16x32_bf16 v[8:11], v[172:175], v[214:217], v[8:11]
	v_mfma_f32_16x16x32_bf16 v[0:3], v[180:183], v[214:217], v[0:3]
	v_mfma_f32_16x16x32_bf16 v[56:59], v[176:179], v[194:197], v[56:59]
	v_mfma_f32_16x16x32_bf16 v[48:51], v[184:187], v[194:197], v[48:51]
	v_mfma_f32_16x16x32_bf16 v[40:43], v[176:179], v[202:205], v[40:43]
	v_mfma_f32_16x16x32_bf16 v[32:35], v[184:187], v[202:205], v[32:35]
	v_mfma_f32_16x16x32_bf16 v[24:27], v[176:179], v[210:213], v[24:27]
	v_mfma_f32_16x16x32_bf16 v[16:19], v[184:187], v[210:213], v[16:19]
	v_mfma_f32_16x16x32_bf16 v[8:11], v[176:179], v[218:221], v[8:11]
	v_mfma_f32_16x16x32_bf16 v[0:3], v[184:187], v[218:221], v[0:3]
	s_setprio 0
	s_barrier
	s_add_i32 s72, 0, 0x18000
	s_add_i32 s73, 0, 0x1c000
	v_add_u32_e32 v158, s72, v165
	v_add_u32_e32 v184, s73, v165
	ds_read_b128 v[146:149], v158
	ds_read_b128 v[150:153], v158 offset:1024
	ds_read_b128 v[154:157], v158 offset:2048
	ds_read_b128 v[158:161], v158 offset:3072
	ds_read_b128 v[172:175], v184
	ds_read_b128 v[176:179], v184 offset:1024
	ds_read_b128 v[180:183], v184 offset:2048
	ds_read_b128 v[184:187], v184 offset:3072
	s_add_u32 s38, s38, s10
	s_addc_u32 s39, s39, s11
	s_mov_b32 m0, s56
	v_lshl_add_u64 v[232:233], s[38:39], 0, v[134:135]
	ds_read_b128 v[188:191], v169 offset:32768
	ds_read_b128 v[194:197], v169 offset:33792
	ds_read_b128 v[198:201], v169 offset:34816
	ds_read_b128 v[202:205], v169 offset:35840
	ds_read_b128 v[206:209], v169 offset:36864
	ds_read_b128 v[210:213], v169 offset:37888
	ds_read_b128 v[214:217], v169 offset:38912
	ds_read_b128 v[218:221], v169 offset:39936
	global_load_lds_dwordx4 v[232:233], off
	v_lshl_add_u64 v[232:233], s[38:39], 0, v[130:131]
	s_mov_b32 m0, s57
	s_nop 0
	global_load_lds_dwordx4 v[232:233], off
	s_waitcnt vmcnt(8)
	s_waitcnt lgkmcnt(0)
	s_barrier
	s_setprio 1
	s_waitcnt lgkmcnt(0)
	v_mfma_f32_16x16x32_bf16 v[120:123], v[146:149], v[188:191], v[120:123]
	v_mfma_f32_16x16x32_bf16 v[116:119], v[154:157], v[188:191], v[116:119]
	v_mfma_f32_16x16x32_bf16 v[108:111], v[146:149], v[198:201], v[108:111]
	v_mfma_f32_16x16x32_bf16 v[100:103], v[154:157], v[198:201], v[100:103]
	v_mfma_f32_16x16x32_bf16 v[92:95], v[146:149], v[206:209], v[92:95]
	v_mfma_f32_16x16x32_bf16 v[84:87], v[154:157], v[206:209], v[84:87]
	v_mfma_f32_16x16x32_bf16 v[76:79], v[146:149], v[214:217], v[76:79]
	v_mfma_f32_16x16x32_bf16 v[68:71], v[154:157], v[214:217], v[68:71]
	v_mfma_f32_16x16x32_bf16 v[120:123], v[150:153], v[194:197], v[120:123]
	v_mfma_f32_16x16x32_bf16 v[116:119], v[158:161], v[194:197], v[116:119]
	v_mfma_f32_16x16x32_bf16 v[108:111], v[150:153], v[202:205], v[108:111]
	v_mfma_f32_16x16x32_bf16 v[100:103], v[158:161], v[202:205], v[100:103]
	v_mfma_f32_16x16x32_bf16 v[92:95], v[150:153], v[210:213], v[92:95]
	v_mfma_f32_16x16x32_bf16 v[84:87], v[158:161], v[210:213], v[84:87]
	v_mfma_f32_16x16x32_bf16 v[76:79], v[150:153], v[218:221], v[76:79]
	v_mfma_f32_16x16x32_bf16 v[68:71], v[158:161], v[218:221], v[68:71]
	s_setprio 0
	s_setprio 1
	v_mfma_f32_16x16x32_bf16 v[124:127], v[172:175], v[188:191], v[124:127]
	v_mfma_f32_16x16x32_bf16 v[112:115], v[180:183], v[188:191], v[112:115]
	v_mfma_f32_16x16x32_bf16 v[104:107], v[172:175], v[198:201], v[104:107]
	v_mfma_f32_16x16x32_bf16 v[96:99], v[180:183], v[198:201], v[96:99]
	v_mfma_f32_16x16x32_bf16 v[88:91], v[172:175], v[206:209], v[88:91]
	v_mfma_f32_16x16x32_bf16 v[80:83], v[180:183], v[206:209], v[80:83]
	v_mfma_f32_16x16x32_bf16 v[72:75], v[172:175], v[214:217], v[72:75]
	v_mfma_f32_16x16x32_bf16 v[64:67], v[180:183], v[214:217], v[64:67]
	v_mfma_f32_16x16x32_bf16 v[124:127], v[176:179], v[194:197], v[124:127]
	v_mfma_f32_16x16x32_bf16 v[112:115], v[184:187], v[194:197], v[112:115]
	v_mfma_f32_16x16x32_bf16 v[104:107], v[176:179], v[202:205], v[104:107]
	v_mfma_f32_16x16x32_bf16 v[96:99], v[184:187], v[202:205], v[96:99]
	v_mfma_f32_16x16x32_bf16 v[88:91], v[176:179], v[210:213], v[88:91]
	v_mfma_f32_16x16x32_bf16 v[80:83], v[184:187], v[210:213], v[80:83]
	v_mfma_f32_16x16x32_bf16 v[72:75], v[176:179], v[218:221], v[72:75]
	v_mfma_f32_16x16x32_bf16 v[64:67], v[184:187], v[218:221], v[64:67]
	s_setprio 0
	s_barrier
; #define PG8_STAGE(bufoff, gbase, voff) do { _Pragma("unroll") for (int _i = 0; _i < 2; ++_i) \
;         __builtin_amdgcn_global_load_lds((const unsigned*)((const char*)(gbase) + (voff)[_i]), (PG8_LAS unsigned*)(lds + (bufoff) + ldsw + _i * 8192), 16, 0, 0); } while (0)
; #define PG8_LDA(dst, b, h) do { _Pragma("unroll") for (int m = 0; m < 4; ++m) _Pragma("unroll") for (int k = 0; k < 2; ++k) dst[m][k] = *(const PG8_LAS bf16x8*)(lds + PG8_SA(b, h) + aoff + m * 2048 + k * 1024); } while (0)
; #define PG8_MMA(ai, bj, At, Bt) do { __builtin_amdgcn_s_setprio(1); _Pragma("unroll") for (int m = 0; m < 4; ++m) _Pragma("unroll") for (int n = 0; n < 2; ++n) _Pragma("unroll") for (int k = 0; k < 2; ++k) \
;         acc[ai][bj][m][n] = __builtin_amdgcn_mfma_f32_16x16x32_bf16(Bt[n][k], At[m][k], acc[ai][bj][m][n], 0, 0, 0); __builtin_amdgcn_s_setprio(0); } while (0)
; #define PG8_WAIT_V(n) asm volatile("s_waitcnt vmcnt(" #n ")" ::: "memory")
; #define PG8_WAIT_L(n) asm volatile("s_waitcnt lgkmcnt(" #n ")" ::: "memory")
; #define PG8_BAR __builtin_amdgcn_s_barrier()
; #define PG8_SCHED __builtin_amdgcn_sched_barrier(0)
; template <class Epi, class Sched, bool ALIGN_EPI = false, bool SP2 = false>
; __device__ __forceinline__ void gemm_phase(PG8_LAS unsigned char* lds, const Gemm g, const Sched& S, const Epi& E) {
;     ...
;         for (int t = 0; t < nt; t += 2) {
;     ...
;             PG8_LDA(At, 1, 1); PG8_STAGE(PG8_SB(1, 0), b3, voffB); PG8_STAGE(PG8_SB(1, 1), b3 + hstep, voffB); PG8_STAGE(PG8_SA(1, 0), a3, voffA);
;             PG8_WAIT_V(8); PG8_WAIT_L(0); PG8_BAR; PG8_MMA(1, 0, At, B0); PG8_MMA(1, 1, At, B1); PG8_BAR; PG8_SCHED;
	s_add_i32 s38, s72, s41
	v_lshl_add_u64 v[162:163], v[162:163], 0, s[16:17]
	s_mov_b32 m0, s38
	ds_read_b128 v[188:191], v169 offset:49152
	ds_read_b128 v[194:197], v169 offset:50176
	ds_read_b128 v[198:201], v169 offset:51200
	ds_read_b128 v[202:205], v169 offset:52224
	ds_read_b128 v[206:209], v169 offset:53248
	ds_read_b128 v[210:213], v169 offset:54272
	ds_read_b128 v[214:217], v169 offset:55296
	ds_read_b128 v[218:221], v169 offset:56320
	global_load_lds_dwordx4 v[162:163], off
	v_lshl_add_u64 v[162:163], v[222:223], 0, s[16:17]
	s_add_i32 m0, s38, 0x2000
	s_add_i32 s38, s73, s41
	global_load_lds_dwordx4 v[162:163], off
	v_lshl_add_u64 v[162:163], v[224:225], 0, s[16:17]
	s_mov_b32 m0, s38
	s_nop 0
	global_load_lds_dwordx4 v[162:163], off
	v_lshl_add_u64 v[162:163], v[226:227], 0, s[16:17]
	s_add_i32 m0, s38, 0x2000
	s_nop 0
	global_load_lds_dwordx4 v[162:163], off
	v_lshl_add_u64 v[162:163], v[228:229], 0, s[16:17]
	s_mov_b32 m0, s59
	s_nop 0
	global_load_lds_dwordx4 v[162:163], off
	v_lshl_add_u64 v[162:163], v[230:231], 0, s[16:17]
	s_mov_b32 m0, s60
	s_nop 0
	global_load_lds_dwordx4 v[162:163], off
	s_waitcnt vmcnt(8)
	s_waitcnt lgkmcnt(0)
	s_barrier
	s_setprio 1
	s_waitcnt lgkmcnt(0)
	v_mfma_f32_16x16x32_bf16 v[60:63], v[146:149], v[188:191], v[60:63]
	v_mfma_f32_16x16x32_bf16 v[52:55], v[154:157], v[188:191], v[52:55]
	v_mfma_f32_16x16x32_bf16 v[44:47], v[146:149], v[198:201], v[44:47]
	v_mfma_f32_16x16x32_bf16 v[36:39], v[154:157], v[198:201], v[36:39]
	v_mfma_f32_16x16x32_bf16 v[28:31], v[146:149], v[206:209], v[28:31]
	v_mfma_f32_16x16x32_bf16 v[20:23], v[154:157], v[206:209], v[20:23]
	v_mfma_f32_16x16x32_bf16 v[12:15], v[146:149], v[214:217], v[12:15]
	v_mfma_f32_16x16x32_bf16 v[4:7], v[154:157], v[214:217], v[4:7]
	v_mfma_f32_16x16x32_bf16 v[60:63], v[150:153], v[194:197], v[60:63]
	v_mfma_f32_16x16x32_bf16 v[52:55], v[158:161], v[194:197], v[52:55]
	v_mfma_f32_16x16x32_bf16 v[44:47], v[150:153], v[202:205], v[44:47]
	v_mfma_f32_16x16x32_bf16 v[36:39], v[158:161], v[202:205], v[36:39]
	v_mfma_f32_16x16x32_bf16 v[28:31], v[150:153], v[210:213], v[28:31]
	v_mfma_f32_16x16x32_bf16 v[20:23], v[158:161], v[210:213], v[20:23]
	v_mfma_f32_16x16x32_bf16 v[12:15], v[150:153], v[218:221], v[12:15]
	v_mfma_f32_16x16x32_bf16 v[4:7], v[158:161], v[218:221], v[4:7]
	s_setprio 0
	s_setprio 1
	v_mfma_f32_16x16x32_bf16 v[56:59], v[172:175], v[188:191], v[56:59]
	v_mfma_f32_16x16x32_bf16 v[48:51], v[180:183], v[188:191], v[48:51]
	v_mfma_f32_16x16x32_bf16 v[40:43], v[172:175], v[198:201], v[40:43]
	v_mfma_f32_16x16x32_bf16 v[32:35], v[180:183], v[198:201], v[32:35]
	v_mfma_f32_16x16x32_bf16 v[24:27], v[172:175], v[206:209], v[24:27]
	v_mfma_f32_16x16x32_bf16 v[16:19], v[180:183], v[206:209], v[16:19]
	v_mfma_f32_16x16x32_bf16 v[8:11], v[172:175], v[214:217], v[8:11]
	v_mfma_f32_16x16x32_bf16 v[0:3], v[180:183], v[214:217], v[0:3]
	v_mfma_f32_16x16x32_bf16 v[56:59], v[176:179], v[194:197], v[56:59]
	v_mfma_f32_16x16x32_bf16 v[48:51], v[184:187], v[194:197], v[48:51]
	v_mfma_f32_16x16x32_bf16 v[40:43], v[176:179], v[202:205], v[40:43]
	v_mfma_f32_16x16x32_bf16 v[32:35], v[184:187], v[202:205], v[32:35]
	v_mfma_f32_16x16x32_bf16 v[24:27], v[176:179], v[210:213], v[24:27]
	v_mfma_f32_16x16x32_bf16 v[16:19], v[184:187], v[210:213], v[16:19]
	v_mfma_f32_16x16x32_bf16 v[8:11], v[176:179], v[218:221], v[8:11]
	v_mfma_f32_16x16x32_bf16 v[0:3], v[184:187], v[218:221], v[0:3]
	s_setprio 0
	s_barrier
	s_add_u32 s36, s36, 0x100
	s_addc_u32 s37, s37, 0
	s_add_u32 s33, s33, 0x100
	s_addc_u32 s70, s70, 0
	s_cmp_ge_i32 s71, s61
	s_mov_b32 s38, s71
	s_cbranch_scc0 .LBB0_1014

; __device__ __forceinline__ void row_rs8(const float* SS, int row0, int fq, float (&rsv)[2][4]) {
;     f32x4 q[2][4];
; #pragma unroll
;     for (int ai = 0; ai < 2; ++ai)
; #pragma unroll
;         for (int m = 0; m < 4; ++m) q[ai][m] = *(const f32x4*)(SS + (size_t)(row0 + ai * HALF + m * 16) * 16 + 4 * fq);
; #pragma unroll
;     for (int ai = 0; ai < 2; ++ai)
; #pragma unroll
;         for (int m = 0; m < 4; ++m) { float t = (q[ai][m][0] + q[ai][m][1]) + (q[ai][m][2] + q[ai][m][3]); t += __shfl_xor(t, 16); t += __shfl_xor(t, 32); rsv[ai][m] = __builtin_amdgcn_rsqf(t * (1.0f / 1024.0f) + 1e-6f); }
; }
;     __device__ __forceinline__ void operator()(const f32x4 (&acc)[2][2][4][2], const Unit& u, int wr, int wc, int fr, int fq) const {
;         const int row0 = u.pm * BM + wr * 64 + fr, col0 = u.pn * HALF + wc * 32 + 8 * fq;
;         float rsv[2][4]; row_rs8(SS, row0, fq, rsv);
; #pragma unroll
;         for (int ai = 0; ai < 2; ++ai)
; #pragma unroll
;             for (int m = 0; m < 4; ++m) {
;                 const int r = row0 + ai * HALF + m * 16; const float rs = rsv[ai][m], nrs = rs * -1.4426950408889634f, rs2 = rs * rs;
;                 float o[8];
; #pragma unroll
;                 for (int n = 0; n < 2; ++n) {
;                     const f32x4 t = acc[ai][0][m][n] * nrs, p = (acc[ai][0][m][n] * acc[ai][1][m][n]) * rs2;
.LBB0_1017:
	v_lshl_add_u32 v162, s4, 8, v164
	v_and_b32_e32 v244, 48, v192
	v_lshl_add_u32 v244, v164, 6, v244
	v_add_u32_e32 v244, 0x20000, v244
	ds_read_b128 v[174:177], v244
	ds_read_b128 v[178:181], v244 offset:1024
	ds_read_b128 v[182:185], v244 offset:2048
	ds_read_b128 v[186:189], v244 offset:3072
	ds_read_b128 v[194:197], v244 offset:8192
	ds_read_b128 v[198:201], v244 offset:9216
	ds_read_b128 v[202:205], v244 offset:10240
	ds_read_b128 v[206:209], v244 offset:11264
	v_xor_b32_e32 v210, 16, v170
	v_xor_b32_e32 v211, 32, v170
	v_lshlrev_b32_e32 v210, 2, v210
	v_lshlrev_b32_e32 v211, 2, v211
	v_or_b32_e32 v160, 16, v162
	v_or_b32_e32 v158, 32, v162
	v_or_b32_e32 v156, 48, v162
	v_add_u32_e32 v154, 0x80, v162
	v_add_u32_e32 v152, 0x90, v162
	v_add_u32_e32 v150, 0xa0, v162
	v_add_u32_e32 v148, 0xb0, v162
	v_lshl_or_b32 v242, s5, 7, v166
	v_lshlrev_b32_e32 v242, 1, v242
	v_mov_b32_e32 v243, 0
	v_mov_b64_e32 v[220:221], s[52:53]
	s_and_b64 vcc, exec, s[0:1]
	s_mov_b64 s[0:1], -1
	v_pk_mul_f32 v[124:125], v[124:125], v[120:121]
	v_pk_mul_f32 v[126:127], v[126:127], v[122:123]
	v_pk_mul_f32 v[112:113], v[112:113], v[116:117]
	v_pk_mul_f32 v[114:115], v[114:115], v[118:119]
	v_pk_mul_f32 v[104:105], v[104:105], v[108:109]
	v_pk_mul_f32 v[106:107], v[106:107], v[110:111]
	v_pk_mul_f32 v[96:97], v[96:97], v[100:101]
	v_pk_mul_f32 v[98:99], v[98:99], v[102:103]
	v_pk_mul_f32 v[88:89], v[88:89], v[92:93]
	v_pk_mul_f32 v[90:91], v[90:91], v[94:95]
	v_pk_mul_f32 v[80:81], v[80:81], v[84:85]
	v_pk_mul_f32 v[82:83], v[82:83], v[86:87]
	v_pk_mul_f32 v[72:73], v[72:73], v[76:77]
	v_pk_mul_f32 v[74:75], v[74:75], v[78:79]
	v_pk_mul_f32 v[64:65], v[64:65], v[68:69]
	v_pk_mul_f32 v[66:67], v[66:67], v[70:71]
	v_pk_mul_f32 v[56:57], v[56:57], v[60:61]
	v_pk_mul_f32 v[58:59], v[58:59], v[62:63]
	v_pk_mul_f32 v[48:49], v[48:49], v[52:53]
	v_pk_mul_f32 v[50:51], v[50:51], v[54:55]
	v_pk_mul_f32 v[40:41], v[40:41], v[44:45]
	v_pk_mul_f32 v[42:43], v[42:43], v[46:47]
	v_pk_mul_f32 v[32:33], v[32:33], v[36:37]
	v_pk_mul_f32 v[34:35], v[34:35], v[38:39]
	v_pk_mul_f32 v[24:25], v[24:25], v[28:29]
	v_pk_mul_f32 v[26:27], v[26:27], v[30:31]
	v_pk_mul_f32 v[16:17], v[16:17], v[20:21]
	v_pk_mul_f32 v[18:19], v[18:19], v[22:23]
	v_pk_mul_f32 v[8:9], v[8:9], v[12:13]
	v_pk_mul_f32 v[10:11], v[10:11], v[14:15]
	v_pk_mul_f32 v[0:1], v[0:1], v[4:5]
	v_pk_mul_f32 v[2:3], v[2:3], v[6:7]
	s_waitcnt lgkmcnt(0)
	v_pk_add_f32 v[174:175], v[174:175], v[176:177]
	v_pk_add_f32 v[178:179], v[178:179], v[180:181]
	v_pk_add_f32 v[182:183], v[182:183], v[184:185]
	v_pk_add_f32 v[186:187], v[186:187], v[188:189]
	v_pk_add_f32 v[194:195], v[194:195], v[196:197]
	v_pk_add_f32 v[198:199], v[198:199], v[200:201]
	v_pk_add_f32 v[202:203], v[202:203], v[204:205]
	v_pk_add_f32 v[206:207], v[206:207], v[208:209]
	v_add_f32_e32 v212, v174, v175
	v_add_f32_e32 v213, v178, v179
	v_add_f32_e32 v214, v182, v183
	v_add_f32_e32 v215, v186, v187
	v_add_f32_e32 v216, v194, v195
	v_add_f32_e32 v217, v198, v199
	v_add_f32_e32 v218, v202, v203
	v_add_f32_e32 v219, v206, v207
	ds_bpermute_b32 v222, v210, v212
	ds_bpermute_b32 v223, v210, v213
	ds_bpermute_b32 v224, v210, v214
	ds_bpermute_b32 v225, v210, v215
	ds_bpermute_b32 v226, v210, v216
	ds_bpermute_b32 v227, v210, v217
	ds_bpermute_b32 v228, v210, v218
	ds_bpermute_b32 v229, v210, v219
	s_waitcnt lgkmcnt(7)
	v_add_f32_e32 v212, v212, v222
	s_waitcnt lgkmcnt(6)
	v_add_f32_e32 v213, v213, v223
	s_waitcnt lgkmcnt(5)
	v_add_f32_e32 v214, v214, v224
	s_waitcnt lgkmcnt(4)
	v_add_f32_e32 v215, v215, v225
	s_waitcnt lgkmcnt(3)
	v_add_f32_e32 v216, v216, v226
	s_waitcnt lgkmcnt(2)
	v_add_f32_e32 v217, v217, v227
	s_waitcnt lgkmcnt(1)
	v_add_f32_e32 v218, v218, v228
	s_waitcnt lgkmcnt(0)
	v_add_f32_e32 v219, v219, v229
	ds_bpermute_b32 v222, v211, v212
	ds_bpermute_b32 v223, v211, v213
	ds_bpermute_b32 v224, v211, v214
	ds_bpermute_b32 v225, v211, v215
	ds_bpermute_b32 v226, v211, v216
	ds_bpermute_b32 v227, v211, v217
	ds_bpermute_b32 v228, v211, v218
	ds_bpermute_b32 v229, v211, v219
	s_waitcnt lgkmcnt(7)
	v_add_f32_e32 v212, v212, v222
	s_waitcnt lgkmcnt(6)
	v_add_f32_e32 v213, v213, v223
	s_waitcnt lgkmcnt(5)
	v_add_f32_e32 v214, v214, v224
	s_waitcnt lgkmcnt(4)
	v_add_f32_e32 v215, v215, v225
	s_waitcnt lgkmcnt(3)
	v_add_f32_e32 v216, v216, v226
	s_waitcnt lgkmcnt(2)
	v_add_f32_e32 v217, v217, v227
	s_waitcnt lgkmcnt(1)
	v_add_f32_e32 v218, v218, v228
	s_waitcnt lgkmcnt(0)
; __device__ __forceinline__ unsigned cvt_pk_bf16(float lo, float hi) { unsigned r; asm volatile("v_cvt_pk_bf16_f32 %0, %1, %2" : "=v"(r) : "v"(lo), "v"(hi)); return r; }
; __device__ __forceinline__ float fast_rcp(float x) { return __builtin_amdgcn_rcpf(x); }
; __device__ __forceinline__ unsigned cvt_pk_bf16(float lo, float hi) { const f32x2 v = {lo, hi}; const bf16x2_t b = __builtin_convertvector(v, bf16x2_t); return __builtin_bit_cast(unsigned, b); }
; __device__ __forceinline__ void row_rs8(const float* SS, int row0, int fq, float (&rsv)[2][4]) {
;     ...
;         for (int m = 0; m < 4; ++m) { float t = (q[ai][m][0] + q[ai][m][1]) + (q[ai][m][2] + q[ai][m][3]); t += __shfl_xor(t, 16); t += __shfl_xor(t, 32); rsv[ai][m] = __builtin_amdgcn_rsqf(t * (1.0f / 1024.0f) + 1e-6f); }
;     __device__ __forceinline__ void operator()(const f32x4 (&acc)[2][2][4][2], const Unit& u, int wr, int wc, int fr, int fq) const {
;     ...
;                 const int r = row0 + ai * HALF + m * 16; const float rs = rsv[ai][m], nrs = rs * -1.4426950408889634f, rs2 = rs * rs;
;                 float o[8];
; #pragma unroll
;                 for (int n = 0; n < 2; ++n) {
;                     const f32x4 t = acc[ai][0][m][n] * nrs, p = (acc[ai][0][m][n] * acc[ai][1][m][n]) * rs2;
; #pragma unroll
;                     for (int j = 0; j < 4; ++j) o[4 * n + j] = p[j] * fast_rcp(1.0f + __builtin_amdgcn_exp2f(t[j]));
;                 }
;                 u32x4 w; w.x = cvt_pk_bf16(o[0], o[1]); w.y = cvt_pk_bf16(o[2], o[3]); w.z = cvt_pk_bf16(o[4], o[5]); w.w = cvt_pk_bf16(o[6], o[7]);
;                 *(u32x4*)(O + (size_t)r * ldo + col0) = w;
	v_add_f32_e32 v219, v219, v229
	v_fmamk_f32 v212, v212, 0x3a800000, v171
	v_fmamk_f32 v213, v213, 0x3a800000, v171
	v_fmamk_f32 v214, v214, 0x3a800000, v171
	v_fmamk_f32 v215, v215, 0x3a800000, v171
	v_fmamk_f32 v216, v216, 0x3a800000, v171
	v_fmamk_f32 v217, v217, 0x3a800000, v171
	v_fmamk_f32 v218, v218, 0x3a800000, v171
	v_fmamk_f32 v219, v219, 0x3a800000, v171
	v_rsq_f32_e32 v212, v212
	v_rsq_f32_e32 v213, v213
	v_rsq_f32_e32 v214, v214
	v_rsq_f32_e32 v215, v215
	v_rsq_f32_e32 v216, v216
	v_rsq_f32_e32 v217, v217
	v_rsq_f32_e32 v218, v218
	v_rsq_f32_e32 v219, v219
	v_mul_f32_e32 v230, 0xbfb8aa3b, v212
	v_mul_f32_e32 v231, v212, v212
	v_mul_f32_e32 v232, 0xbfb8aa3b, v213
	v_mul_f32_e32 v233, v213, v213
	v_mul_f32_e32 v234, 0xbfb8aa3b, v214
	v_mul_f32_e32 v235, v214, v214
	v_mul_f32_e32 v184, 0xbfb8aa3b, v215
	v_mul_f32_e32 v185, v215, v215
	v_mul_f32_e32 v186, 0xbfb8aa3b, v216
	v_mul_f32_e32 v187, v216, v216
	v_mul_f32_e32 v188, 0xbfb8aa3b, v217
	v_mul_f32_e32 v189, v217, v217
	v_mul_f32_e32 v190, 0xbfb8aa3b, v218
	v_mul_f32_e32 v191, v218, v218
	v_mul_f32_e32 v204, 0xbfb8aa3b, v219
	v_mul_f32_e32 v205, v219, v219
	v_pk_mul_f32 v[120:121], v[120:121], v[230:231] op_sel_hi:[1,0]
	v_pk_mul_f32 v[122:123], v[122:123], v[230:231] op_sel_hi:[1,0]
	v_pk_mul_f32 v[116:117], v[116:117], v[230:231] op_sel_hi:[1,0]
	v_pk_mul_f32 v[118:119], v[118:119], v[230:231] op_sel_hi:[1,0]
	v_exp_f32_e32 v120, v120
	v_exp_f32_e32 v121, v121
	v_exp_f32_e32 v122, v122
	v_exp_f32_e32 v123, v123
	v_exp_f32_e32 v116, v116
	v_exp_f32_e32 v117, v117
	v_exp_f32_e32 v118, v118
	v_exp_f32_e32 v119, v119
	v_pk_mul_f32 v[124:125], v[124:125], v[230:231] op_sel:[0,1] op_sel_hi:[1,1]
	v_pk_mul_f32 v[126:127], v[126:127], v[230:231] op_sel:[0,1] op_sel_hi:[1,1]
	v_pk_mul_f32 v[112:113], v[112:113], v[230:231] op_sel:[0,1] op_sel_hi:[1,1]
	v_pk_mul_f32 v[114:115], v[114:115], v[230:231] op_sel:[0,1] op_sel_hi:[1,1]
	v_pk_add_f32 v[120:121], v[120:121], 1.0 op_sel_hi:[1,0]
	v_pk_add_f32 v[122:123], v[122:123], 1.0 op_sel_hi:[1,0]
	v_pk_add_f32 v[116:117], v[116:117], 1.0 op_sel_hi:[1,0]
	v_pk_add_f32 v[118:119], v[118:119], 1.0 op_sel_hi:[1,0]
	v_rcp_f32_e32 v120, v120
	v_rcp_f32_e32 v121, v121
	v_rcp_f32_e32 v122, v122
	v_rcp_f32_e32 v123, v123
	v_rcp_f32_e32 v116, v116
	v_rcp_f32_e32 v117, v117
	v_rcp_f32_e32 v118, v118
	v_rcp_f32_e32 v119, v119
	v_mad_i64_i32 v[208:209], s[4:5], v162, s67, v[220:221]
	v_lshl_add_u64 v[208:209], v[208:209], 0, v[242:243]
	v_pk_mul_f32 v[124:125], v[124:125], v[120:121]
	v_pk_mul_f32 v[126:127], v[126:127], v[122:123]
	v_pk_mul_f32 v[112:113], v[112:113], v[116:117]
	v_pk_mul_f32 v[114:115], v[114:115], v[118:119]
	v_cvt_pk_bf16_f32 v120, v124, v125
	v_cvt_pk_bf16_f32 v121, v126, v127
	v_cvt_pk_bf16_f32 v122, v112, v113
	v_cvt_pk_bf16_f32 v123, v114, v115
	global_store_dwordx4 v[208:209], v[120:123], off
	v_pk_mul_f32 v[108:109], v[108:109], v[232:233] op_sel_hi:[1,0]
	v_pk_mul_f32 v[110:111], v[110:111], v[232:233] op_sel_hi:[1,0]
	v_pk_mul_f32 v[100:101], v[100:101], v[232:233] op_sel_hi:[1,0]
	v_pk_mul_f32 v[102:103], v[102:103], v[232:233] op_sel_hi:[1,0]
	v_exp_f32_e32 v108, v108
	v_exp_f32_e32 v109, v109
	v_exp_f32_e32 v110, v110
	v_exp_f32_e32 v111, v111
	v_exp_f32_e32 v100, v100
	v_exp_f32_e32 v101, v101
	v_exp_f32_e32 v102, v102
	v_exp_f32_e32 v103, v103
	v_pk_mul_f32 v[104:105], v[104:105], v[232:233] op_sel:[0,1] op_sel_hi:[1,1]
	v_pk_mul_f32 v[106:107], v[106:107], v[232:233] op_sel:[0,1] op_sel_hi:[1,1]
	v_pk_mul_f32 v[96:97], v[96:97], v[232:233] op_sel:[0,1] op_sel_hi:[1,1]
	v_pk_mul_f32 v[98:99], v[98:99], v[232:233] op_sel:[0,1] op_sel_hi:[1,1]
	v_pk_add_f32 v[108:109], v[108:109], 1.0 op_sel_hi:[1,0]
	v_pk_add_f32 v[110:111], v[110:111], 1.0 op_sel_hi:[1,0]
	v_pk_add_f32 v[100:101], v[100:101], 1.0 op_sel_hi:[1,0]
	v_pk_add_f32 v[102:103], v[102:103], 1.0 op_sel_hi:[1,0]
	v_rcp_f32_e32 v108, v108
	v_rcp_f32_e32 v109, v109
	v_rcp_f32_e32 v110, v110
	v_rcp_f32_e32 v111, v111
	v_rcp_f32_e32 v100, v100
	v_rcp_f32_e32 v101, v101
	v_rcp_f32_e32 v102, v102
	v_rcp_f32_e32 v103, v103
	v_mad_i64_i32 v[208:209], s[4:5], v160, s67, v[220:221]
	v_lshl_add_u64 v[208:209], v[208:209], 0, v[242:243]
	v_pk_mul_f32 v[104:105], v[104:105], v[108:109]
	v_pk_mul_f32 v[106:107], v[106:107], v[110:111]
	v_pk_mul_f32 v[96:97], v[96:97], v[100:101]
	v_pk_mul_f32 v[98:99], v[98:99], v[102:103]
	v_cvt_pk_bf16_f32 v108, v104, v105
	v_cvt_pk_bf16_f32 v109, v106, v107
	v_cvt_pk_bf16_f32 v110, v96, v97
	v_cvt_pk_bf16_f32 v111, v98, v99
	global_store_dwordx4 v[208:209], v[108:111], off
	v_pk_mul_f32 v[92:93], v[92:93], v[234:235] op_sel_hi:[1,0]
	v_pk_mul_f32 v[94:95], v[94:95], v[234:235] op_sel_hi:[1,0]
	v_pk_mul_f32 v[84:85], v[84:85], v[234:235] op_sel_hi:[1,0]
	v_pk_mul_f32 v[86:87], v[86:87], v[234:235] op_sel_hi:[1,0]
	v_exp_f32_e32 v92, v92
	v_exp_f32_e32 v93, v93
	v_exp_f32_e32 v94, v94
	v_exp_f32_e32 v95, v95
	v_exp_f32_e32 v84, v84
	v_exp_f32_e32 v85, v85
	v_exp_f32_e32 v86, v86
	v_exp_f32_e32 v87, v87
	v_pk_mul_f32 v[88:89], v[88:89], v[234:235] op_sel:[0,1] op_sel_hi:[1,1]
	v_pk_mul_f32 v[90:91], v[90:91], v[234:235] op_sel:[0,1] op_sel_hi:[1,1]
	v_pk_mul_f32 v[80:81], v[80:81], v[234:235] op_sel:[0,1] op_sel_hi:[1,1]
	v_pk_mul_f32 v[82:83], v[82:83], v[234:235] op_sel:[0,1] op_sel_hi:[1,1]
	v_pk_add_f32 v[92:93], v[92:93], 1.0 op_sel_hi:[1,0]
	v_pk_add_f32 v[94:95], v[94:95], 1.0 op_sel_hi:[1,0]
	v_pk_add_f32 v[84:85], v[84:85], 1.0 op_sel_hi:[1,0]
	v_pk_add_f32 v[86:87], v[86:87], 1.0 op_sel_hi:[1,0]
	v_rcp_f32_e32 v92, v92
	v_rcp_f32_e32 v93, v93
	v_rcp_f32_e32 v94, v94
	v_rcp_f32_e32 v95, v95
	v_rcp_f32_e32 v84, v84
	v_rcp_f32_e32 v85, v85
; __device__ __forceinline__ unsigned cvt_pk_bf16(float lo, float hi) { unsigned r; asm volatile("v_cvt_pk_bf16_f32 %0, %1, %2" : "=v"(r) : "v"(lo), "v"(hi)); return r; }
; __device__ __forceinline__ float fast_rcp(float x) { return __builtin_amdgcn_rcpf(x); }
; __device__ __forceinline__ unsigned cvt_pk_bf16(float lo, float hi) { const f32x2 v = {lo, hi}; const bf16x2_t b = __builtin_convertvector(v, bf16x2_t); return __builtin_bit_cast(unsigned, b); }
;     __device__ __forceinline__ void operator()(const f32x4 (&acc)[2][2][4][2], const Unit& u, int wr, int wc, int fr, int fq) const {
;         const int row0 = u.pm * BM + wr * 64 + fr, col0 = u.pn * HALF + wc * 32 + 8 * fq;
;         float rsv[2][4]; row_rs8(SS, row0, fq, rsv);
; #pragma unroll
;         for (int ai = 0; ai < 2; ++ai)
; #pragma unroll
;             for (int m = 0; m < 4; ++m) {
;                 const int r = row0 + ai * HALF + m * 16; const float rs = rsv[ai][m], nrs = rs * -1.4426950408889634f, rs2 = rs * rs;
;                 float o[8];
; #pragma unroll
;                 for (int n = 0; n < 2; ++n) {
;                     const f32x4 t = acc[ai][0][m][n] * nrs, p = (acc[ai][0][m][n] * acc[ai][1][m][n]) * rs2;
; #pragma unroll
;                     for (int j = 0; j < 4; ++j) o[4 * n + j] = p[j] * fast_rcp(1.0f + __builtin_amdgcn_exp2f(t[j]));
;                 }
;                 u32x4 w; w.x = cvt_pk_bf16(o[0], o[1]); w.y = cvt_pk_bf16(o[2], o[3]); w.z = cvt_pk_bf16(o[4], o[5]); w.w = cvt_pk_bf16(o[6], o[7]);
;                 *(u32x4*)(O + (size_t)r * ldo + col0) = w;
;             }
	v_rcp_f32_e32 v86, v86
	v_rcp_f32_e32 v87, v87
	v_mad_i64_i32 v[208:209], s[4:5], v158, s67, v[220:221]
	v_lshl_add_u64 v[208:209], v[208:209], 0, v[242:243]
	v_pk_mul_f32 v[88:89], v[88:89], v[92:93]
	v_pk_mul_f32 v[90:91], v[90:91], v[94:95]
	v_pk_mul_f32 v[80:81], v[80:81], v[84:85]
	v_pk_mul_f32 v[82:83], v[82:83], v[86:87]
	v_cvt_pk_bf16_f32 v92, v88, v89
	v_cvt_pk_bf16_f32 v93, v90, v91
	v_cvt_pk_bf16_f32 v94, v80, v81
	v_cvt_pk_bf16_f32 v95, v82, v83
	global_store_dwordx4 v[208:209], v[92:95], off
	v_pk_mul_f32 v[76:77], v[76:77], v[184:185] op_sel_hi:[1,0]
	v_pk_mul_f32 v[78:79], v[78:79], v[184:185] op_sel_hi:[1,0]
	v_pk_mul_f32 v[68:69], v[68:69], v[184:185] op_sel_hi:[1,0]
	v_pk_mul_f32 v[70:71], v[70:71], v[184:185] op_sel_hi:[1,0]
	v_exp_f32_e32 v76, v76
	v_exp_f32_e32 v77, v77
	v_exp_f32_e32 v78, v78
	v_exp_f32_e32 v79, v79
	v_exp_f32_e32 v68, v68
	v_exp_f32_e32 v69, v69
	v_exp_f32_e32 v70, v70
	v_exp_f32_e32 v71, v71
	v_pk_mul_f32 v[72:73], v[72:73], v[184:185] op_sel:[0,1] op_sel_hi:[1,1]
	v_pk_mul_f32 v[74:75], v[74:75], v[184:185] op_sel:[0,1] op_sel_hi:[1,1]
	v_pk_mul_f32 v[64:65], v[64:65], v[184:185] op_sel:[0,1] op_sel_hi:[1,1]
	v_pk_mul_f32 v[66:67], v[66:67], v[184:185] op_sel:[0,1] op_sel_hi:[1,1]
	v_pk_add_f32 v[76:77], v[76:77], 1.0 op_sel_hi:[1,0]
	v_pk_add_f32 v[78:79], v[78:79], 1.0 op_sel_hi:[1,0]
	v_pk_add_f32 v[68:69], v[68:69], 1.0 op_sel_hi:[1,0]
	v_pk_add_f32 v[70:71], v[70:71], 1.0 op_sel_hi:[1,0]
	v_rcp_f32_e32 v76, v76
	v_rcp_f32_e32 v77, v77
	v_rcp_f32_e32 v78, v78
	v_rcp_f32_e32 v79, v79
	v_rcp_f32_e32 v68, v68
	v_rcp_f32_e32 v69, v69
	v_rcp_f32_e32 v70, v70
	v_rcp_f32_e32 v71, v71
	v_mad_i64_i32 v[208:209], s[4:5], v156, s67, v[220:221]
	v_lshl_add_u64 v[208:209], v[208:209], 0, v[242:243]
	v_pk_mul_f32 v[72:73], v[72:73], v[76:77]
	v_pk_mul_f32 v[74:75], v[74:75], v[78:79]
	v_pk_mul_f32 v[64:65], v[64:65], v[68:69]
	v_pk_mul_f32 v[66:67], v[66:67], v[70:71]
	v_cvt_pk_bf16_f32 v76, v72, v73
	v_cvt_pk_bf16_f32 v77, v74, v75
	v_cvt_pk_bf16_f32 v78, v64, v65
	v_cvt_pk_bf16_f32 v79, v66, v67
	global_store_dwordx4 v[208:209], v[76:79], off
	v_pk_mul_f32 v[60:61], v[60:61], v[186:187] op_sel_hi:[1,0]
	v_pk_mul_f32 v[62:63], v[62:63], v[186:187] op_sel_hi:[1,0]
	v_pk_mul_f32 v[52:53], v[52:53], v[186:187] op_sel_hi:[1,0]
	v_pk_mul_f32 v[54:55], v[54:55], v[186:187] op_sel_hi:[1,0]
	v_exp_f32_e32 v60, v60
	v_exp_f32_e32 v61, v61
	v_exp_f32_e32 v62, v62
	v_exp_f32_e32 v63, v63
	v_exp_f32_e32 v52, v52
	v_exp_f32_e32 v53, v53
	v_exp_f32_e32 v54, v54
	v_exp_f32_e32 v55, v55
	v_pk_mul_f32 v[56:57], v[56:57], v[186:187] op_sel:[0,1] op_sel_hi:[1,1]
	v_pk_mul_f32 v[58:59], v[58:59], v[186:187] op_sel:[0,1] op_sel_hi:[1,1]
	v_pk_mul_f32 v[48:49], v[48:49], v[186:187] op_sel:[0,1] op_sel_hi:[1,1]
	v_pk_mul_f32 v[50:51], v[50:51], v[186:187] op_sel:[0,1] op_sel_hi:[1,1]
	v_pk_add_f32 v[60:61], v[60:61], 1.0 op_sel_hi:[1,0]
	v_pk_add_f32 v[62:63], v[62:63], 1.0 op_sel_hi:[1,0]
	v_pk_add_f32 v[52:53], v[52:53], 1.0 op_sel_hi:[1,0]
	v_pk_add_f32 v[54:55], v[54:55], 1.0 op_sel_hi:[1,0]
	v_rcp_f32_e32 v60, v60
	v_rcp_f32_e32 v61, v61
	v_rcp_f32_e32 v62, v62
	v_rcp_f32_e32 v63, v63
	v_rcp_f32_e32 v52, v52
	v_rcp_f32_e32 v53, v53
	v_rcp_f32_e32 v54, v54
	v_rcp_f32_e32 v55, v55
	v_mad_i64_i32 v[208:209], s[4:5], v154, s67, v[220:221]
	v_lshl_add_u64 v[208:209], v[208:209], 0, v[242:243]
	v_pk_mul_f32 v[56:57], v[56:57], v[60:61]
	v_pk_mul_f32 v[58:59], v[58:59], v[62:63]
	v_pk_mul_f32 v[48:49], v[48:49], v[52:53]
	v_pk_mul_f32 v[50:51], v[50:51], v[54:55]
	v_cvt_pk_bf16_f32 v60, v56, v57
	v_cvt_pk_bf16_f32 v61, v58, v59
	v_cvt_pk_bf16_f32 v62, v48, v49
	v_cvt_pk_bf16_f32 v63, v50, v51
	global_store_dwordx4 v[208:209], v[60:63], off
	v_pk_mul_f32 v[44:45], v[44:45], v[188:189] op_sel_hi:[1,0]
	v_pk_mul_f32 v[46:47], v[46:47], v[188:189] op_sel_hi:[1,0]
	v_pk_mul_f32 v[36:37], v[36:37], v[188:189] op_sel_hi:[1,0]
	v_pk_mul_f32 v[38:39], v[38:39], v[188:189] op_sel_hi:[1,0]
	v_exp_f32_e32 v44, v44
	v_exp_f32_e32 v45, v45
	v_exp_f32_e32 v46, v46
	v_exp_f32_e32 v47, v47
	v_exp_f32_e32 v36, v36
	v_exp_f32_e32 v37, v37
	v_exp_f32_e32 v38, v38
	v_exp_f32_e32 v39, v39
	v_pk_mul_f32 v[40:41], v[40:41], v[188:189] op_sel:[0,1] op_sel_hi:[1,1]
	v_pk_mul_f32 v[42:43], v[42:43], v[188:189] op_sel:[0,1] op_sel_hi:[1,1]
; __device__ __forceinline__ unsigned cvt_pk_bf16(float lo, float hi) { unsigned r; asm volatile("v_cvt_pk_bf16_f32 %0, %1, %2" : "=v"(r) : "v"(lo), "v"(hi)); return r; }
; __device__ __forceinline__ float fast_rcp(float x) { return __builtin_amdgcn_rcpf(x); }
; __device__ __forceinline__ unsigned cvt_pk_bf16(float lo, float hi) { const f32x2 v = {lo, hi}; const bf16x2_t b = __builtin_convertvector(v, bf16x2_t); return __builtin_bit_cast(unsigned, b); }
;     __device__ __forceinline__ void operator()(const f32x4 (&acc)[2][2][4][2], const Unit& u, int wr, int wc, int fr, int fq) const {
;     ...
;             for (int m = 0; m < 4; ++m) {
;                 const int r = row0 + ai * HALF + m * 16; const float rs = rsv[ai][m], nrs = rs * -1.4426950408889634f, rs2 = rs * rs;
;                 float o[8];
; #pragma unroll
;                 for (int n = 0; n < 2; ++n) {
;                     const f32x4 t = acc[ai][0][m][n] * nrs, p = (acc[ai][0][m][n] * acc[ai][1][m][n]) * rs2;
; #pragma unroll
;                     for (int j = 0; j < 4; ++j) o[4 * n + j] = p[j] * fast_rcp(1.0f + __builtin_amdgcn_exp2f(t[j]));
;                 }
;                 u32x4 w; w.x = cvt_pk_bf16(o[0], o[1]); w.y = cvt_pk_bf16(o[2], o[3]); w.z = cvt_pk_bf16(o[4], o[5]); w.w = cvt_pk_bf16(o[6], o[7]);
;                 *(u32x4*)(O + (size_t)r * ldo + col0) = w;
;             }
	v_pk_mul_f32 v[32:33], v[32:33], v[188:189] op_sel:[0,1] op_sel_hi:[1,1]
	v_pk_mul_f32 v[34:35], v[34:35], v[188:189] op_sel:[0,1] op_sel_hi:[1,1]
	v_pk_add_f32 v[44:45], v[44:45], 1.0 op_sel_hi:[1,0]
	v_pk_add_f32 v[46:47], v[46:47], 1.0 op_sel_hi:[1,0]
	v_pk_add_f32 v[36:37], v[36:37], 1.0 op_sel_hi:[1,0]
	v_pk_add_f32 v[38:39], v[38:39], 1.0 op_sel_hi:[1,0]
	v_rcp_f32_e32 v44, v44
	v_rcp_f32_e32 v45, v45
	v_rcp_f32_e32 v46, v46
	v_rcp_f32_e32 v47, v47
	v_rcp_f32_e32 v36, v36
	v_rcp_f32_e32 v37, v37
	v_rcp_f32_e32 v38, v38
	v_rcp_f32_e32 v39, v39
	v_mad_i64_i32 v[208:209], s[4:5], v152, s67, v[220:221]
	v_lshl_add_u64 v[208:209], v[208:209], 0, v[242:243]
	v_pk_mul_f32 v[40:41], v[40:41], v[44:45]
	v_pk_mul_f32 v[42:43], v[42:43], v[46:47]
	v_pk_mul_f32 v[32:33], v[32:33], v[36:37]
	v_pk_mul_f32 v[34:35], v[34:35], v[38:39]
	v_cvt_pk_bf16_f32 v44, v40, v41
	v_cvt_pk_bf16_f32 v45, v42, v43
	v_cvt_pk_bf16_f32 v46, v32, v33
	v_cvt_pk_bf16_f32 v47, v34, v35
	global_store_dwordx4 v[208:209], v[44:47], off
	v_pk_mul_f32 v[28:29], v[28:29], v[190:191] op_sel_hi:[1,0]
	v_pk_mul_f32 v[30:31], v[30:31], v[190:191] op_sel_hi:[1,0]
	v_pk_mul_f32 v[20:21], v[20:21], v[190:191] op_sel_hi:[1,0]
	v_pk_mul_f32 v[22:23], v[22:23], v[190:191] op_sel_hi:[1,0]
	v_exp_f32_e32 v28, v28
	v_exp_f32_e32 v29, v29
	v_exp_f32_e32 v30, v30
	v_exp_f32_e32 v31, v31
	v_exp_f32_e32 v20, v20
	v_exp_f32_e32 v21, v21
	v_exp_f32_e32 v22, v22
	v_exp_f32_e32 v23, v23
	v_pk_mul_f32 v[24:25], v[24:25], v[190:191] op_sel:[0,1] op_sel_hi:[1,1]
	v_pk_mul_f32 v[26:27], v[26:27], v[190:191] op_sel:[0,1] op_sel_hi:[1,1]
	v_pk_mul_f32 v[16:17], v[16:17], v[190:191] op_sel:[0,1] op_sel_hi:[1,1]
	v_pk_mul_f32 v[18:19], v[18:19], v[190:191] op_sel:[0,1] op_sel_hi:[1,1]
	v_pk_add_f32 v[28:29], v[28:29], 1.0 op_sel_hi:[1,0]
	v_pk_add_f32 v[30:31], v[30:31], 1.0 op_sel_hi:[1,0]
	v_pk_add_f32 v[20:21], v[20:21], 1.0 op_sel_hi:[1,0]
	v_pk_add_f32 v[22:23], v[22:23], 1.0 op_sel_hi:[1,0]
	v_rcp_f32_e32 v28, v28
	v_rcp_f32_e32 v29, v29
	v_rcp_f32_e32 v30, v30
	v_rcp_f32_e32 v31, v31
	v_rcp_f32_e32 v20, v20
	v_rcp_f32_e32 v21, v21
	v_rcp_f32_e32 v22, v22
	v_rcp_f32_e32 v23, v23
	v_mad_i64_i32 v[208:209], s[4:5], v150, s67, v[220:221]
	v_lshl_add_u64 v[208:209], v[208:209], 0, v[242:243]
	v_pk_mul_f32 v[24:25], v[24:25], v[28:29]
	v_pk_mul_f32 v[26:27], v[26:27], v[30:31]
	v_pk_mul_f32 v[16:17], v[16:17], v[20:21]
	v_pk_mul_f32 v[18:19], v[18:19], v[22:23]
	v_cvt_pk_bf16_f32 v28, v24, v25
	v_cvt_pk_bf16_f32 v29, v26, v27
	v_cvt_pk_bf16_f32 v30, v16, v17
	v_cvt_pk_bf16_f32 v31, v18, v19
	global_store_dwordx4 v[208:209], v[28:31], off
	v_pk_mul_f32 v[12:13], v[12:13], v[204:205] op_sel_hi:[1,0]
	v_pk_mul_f32 v[14:15], v[14:15], v[204:205] op_sel_hi:[1,0]
	v_pk_mul_f32 v[4:5], v[4:5], v[204:205] op_sel_hi:[1,0]
	v_pk_mul_f32 v[6:7], v[6:7], v[204:205] op_sel_hi:[1,0]
	v_exp_f32_e32 v12, v12
	v_exp_f32_e32 v13, v13
	v_exp_f32_e32 v14, v14
	v_exp_f32_e32 v15, v15
	v_exp_f32_e32 v4, v4
	v_exp_f32_e32 v5, v5
	v_exp_f32_e32 v6, v6
	v_exp_f32_e32 v7, v7
	v_pk_mul_f32 v[8:9], v[8:9], v[204:205] op_sel:[0,1] op_sel_hi:[1,1]
	v_pk_mul_f32 v[10:11], v[10:11], v[204:205] op_sel:[0,1] op_sel_hi:[1,1]
	v_pk_mul_f32 v[0:1], v[0:1], v[204:205] op_sel:[0,1] op_sel_hi:[1,1]
	v_pk_mul_f32 v[2:3], v[2:3], v[204:205] op_sel:[0,1] op_sel_hi:[1,1]
	v_pk_add_f32 v[12:13], v[12:13], 1.0 op_sel_hi:[1,0]
	v_pk_add_f32 v[14:15], v[14:15], 1.0 op_sel_hi:[1,0]
	v_pk_add_f32 v[4:5], v[4:5], 1.0 op_sel_hi:[1,0]
	v_pk_add_f32 v[6:7], v[6:7], 1.0 op_sel_hi:[1,0]
	v_rcp_f32_e32 v12, v12
	v_rcp_f32_e32 v13, v13
	v_rcp_f32_e32 v14, v14
	v_rcp_f32_e32 v15, v15
	v_rcp_f32_e32 v4, v4
	v_rcp_f32_e32 v5, v5
	v_rcp_f32_e32 v6, v6
	v_rcp_f32_e32 v7, v7
	v_mad_i64_i32 v[208:209], s[4:5], v148, s67, v[220:221]
	v_lshl_add_u64 v[208:209], v[208:209], 0, v[242:243]
	v_pk_mul_f32 v[8:9], v[8:9], v[12:13]
	v_pk_mul_f32 v[10:11], v[10:11], v[14:15]
	v_pk_mul_f32 v[0:1], v[0:1], v[4:5]
	v_pk_mul_f32 v[2:3], v[2:3], v[6:7]
	v_cvt_pk_bf16_f32 v12, v8, v9
	v_cvt_pk_bf16_f32 v13, v10, v11
	v_cvt_pk_bf16_f32 v14, v0, v1
	v_cvt_pk_bf16_f32 v15, v2, v3
	global_store_dwordx4 v[208:209], v[12:15], off
	s_cbranch_vccnz .LBB0_1005
	s_andn2_b64 vcc, exec, s[14:15]
	s_cbranch_vccnz .LBB0_1004
	s_barrier
	s_branch .LBB0_1004
